# scan: deeper LDS prefetch hoist (after 1st consumer wait); attention flags via ds ops instead of serialized flat loads
# baseline (speedup 1.0000x reference)
; template <int CTRL> __device__ __forceinline__ float dppf(float x) { return __builtin_bit_cast(float, __builtin_amdgcn_mov_dpp(__builtin_bit_cast(int, x), CTRL, 0xf, 0xf, true)); }
; __device__ __forceinline__ void scan_unit(const Params& p, int unit) {
;     ...
;         for (int c = 0; c < SC_NC; ++c) {
;             const float* buf = (const float*)(smem + (c & 1) * SC_BUF);
;             float* yb = (float*)(smem + SC_YOFF + (c & 1) * SC_YBUF);
;             const float* bp = buf + sub * 4;
;     ...
;             f32x4 r1 = SC_LD(0, 0), w1 = SC_LD(1, 0), k1 = SC_LD(2, 0), q1 = SC_LD(3, 0), n1 = SC_LD(4, 0);
;             f32x4 r2 = SC_LD(0, 1), w2 = SC_LD(1, 1), k2 = SC_LD(2, 1), g2 = SC_LD(3, 1), n2 = SC_LD(4, 1);
;             float v1 = buf[SC_VOFF + rl], v2 = buf[SC_VOFF + 16 + rl];
;             f32x2 cf = *(const f32x2*)(buf + SC_COFF);
; #pragma unroll
;             for (int pr = 0; pr < SC_TC / 2; ++pr) {
;                 const int sn = 2 * pr + 2;
;                 const f32x4 r1n = SC_LD(0, sn), w1n = SC_LD(1, sn), k1n = SC_LD(2, sn), q1n = SC_LD(3, sn), n1n = SC_LD(4, sn);
;                 const f32x4 r2n = SC_LD(0, sn + 1), w2n = SC_LD(1, sn + 1), k2n = SC_LD(2, sn + 1), g2n = SC_LD(3, sn + 1), n2n = SC_LD(4, sn + 1);
;                 const float v1n = buf[SC_VOFF + sn * 16 + rl], v2n = buf[SC_VOFF + (sn + 1) * 16 + rl];
;                 const f32x2 cfn = *(const f32x2*)(buf + SC_COFF + (pr + 1) * 2);
;                 __builtin_amdgcn_sched_barrier(0x7);
;                 float d1 = dot4(S, q1), e2 = dot4(S, g2);
;                 const f32x4 t1 = S * w1 + v1 * k1;
;                 reduce16x2(d1, e2);
;                 const float d2 = e2 + v1 * cf[0] - d1 * cf[1];
;                 const f32x4 S1 = t1 + d1 * n1;
;                 const f32x4 S2 = (S1 * w2 + v2 * k2) + d2 * n2;
;                 float y1 = dot4(S1, r1), y2 = dot4(S2, r2);
;                 y1 += dppf<0xB1>(y1); y2 += dppf<0xB1>(y2);
;                 float yz = odd_lane ? y2 : y1;
;                 yz += dppf<0x122>(yz); yz += dppf<0x124>(yz); yz += dppf<0x128>(yz);
;                 yb[(2 * pr) * 16 + yoff] = yz;
.LBB0_786:
	s_and_b32 s5, s4, 1
	s_mul_i32 s6, s5, 0xa880
	v_lshl_add_u32 v6, s5, 11, v5
	s_add_i32 s5, s6, 0
	v_lshl_add_u32 v9, v169, 2, s5
	v_mov_b32_e32 v7, s5
	v_lshl_add_u32 v8, v4, 2, s5
	v_add_u32_e32 v129, 0xa000, v9
	ds_read_b128 v[10:13], v8
	ds_read_b128 v[14:17], v8 offset:256
	ds_read_b128 v[18:21], v8 offset:8192
	ds_read_b128 v[22:25], v8 offset:8448
	ds_read_b128 v[26:29], v8 offset:16384
	ds_read_b128 v[30:33], v8 offset:16640
	ds_read_b128 v[34:37], v8 offset:24576
	ds_read_b128 v[38:41], v8 offset:24832
	ds_read_b128 v[42:45], v8 offset:32768
	ds_read_b128 v[46:49], v8 offset:33024
	ds_read_b128 v[50:53], v7 offset:43008
	ds_read_b128 v[54:57], v8 offset:512
	ds_read_b128 v[58:61], v8 offset:768
	ds_read_b128 v[62:65], v8 offset:8704
	ds_read_b128 v[66:69], v8 offset:8960
	ds_read_b128 v[70:73], v8 offset:16896
	ds_read_b128 v[74:77], v8 offset:17152
	ds_read_b128 v[78:81], v8 offset:25088
	ds_read_b128 v[82:85], v8 offset:25344
	ds_read_b128 v[86:89], v8 offset:33280
	ds_read_b128 v[90:93], v8 offset:33536
	ds_read2_b32 v[126:127], v129 offset1:16
	ds_read2_b32 v[142:143], v129 offset0:32 offset1:48
	s_waitcnt lgkmcnt(14)
	v_pk_mul_f32 v[36:37], v[2:3], v[36:37]
	v_pk_mul_f32 v[40:41], v[2:3], v[40:41]
	v_pk_fma_f32 v[34:35], v[0:1], v[34:35], v[36:37]
	v_pk_fma_f32 v[36:37], v[0:1], v[38:39], v[40:41]
	s_waitcnt lgkmcnt(1)
	ds_read_b128 v[94:97], v8 offset:1024
	ds_read_b128 v[98:101], v8 offset:1280
	ds_read_b128 v[102:105], v8 offset:9216
	ds_read_b128 v[106:109], v8 offset:9472
	ds_read_b128 v[110:113], v8 offset:17408
	ds_read_b128 v[114:117], v8 offset:17664
	ds_read_b128 v[118:121], v8 offset:25600
	ds_read_b128 v[122:125], v8 offset:25856
	ds_read_b128 v[134:137], v8 offset:33792
	ds_read_b128 v[138:141], v8 offset:34048
	ds_read2_b32 v[144:145], v129 offset0:64 offset1:80
	ds_read_b64 v[146:147], v7 offset:43024
	v_pk_mul_f32 v[26:27], v[26:27], v[126:127] op_sel_hi:[1,0]
	v_add_f32_e32 v34, v34, v35
	v_add_f32_e32 v35, v36, v37
	v_pk_fma_f32 v[0:1], v[0:1], v[18:19], v[26:27]
	v_add_f32_dpp v18, v34, v34 quad_perm:[1,0,3,2] row_mask:0xf bank_mask:0xf bound_ctrl:1
	v_add_f32_dpp v19, v35, v35 quad_perm:[1,0,3,2] row_mask:0xf bank_mask:0xf bound_ctrl:1
	v_pk_mul_f32 v[28:29], v[28:29], v[126:127] op_sel_hi:[1,0]
	v_add_f32_dpp v18, v18, v18 quad_perm:[2,3,0,1] row_mask:0xf bank_mask:0xf bound_ctrl:1
	v_add_f32_dpp v19, v19, v19 quad_perm:[2,3,0,1] row_mask:0xf bank_mask:0xf bound_ctrl:1
	v_mov_b32_e32 v38, v127
	v_add_f32_dpp v18, v18, v18 row_half_mirror row_mask:0xf bank_mask:0xf bound_ctrl:1
	v_add_f32_dpp v19, v19, v19 row_half_mirror row_mask:0xf bank_mask:0xf bound_ctrl:1
	v_pk_fma_f32 v[2:3], v[2:3], v[20:21], v[28:29]
	v_add_f32_dpp v127, v18, v18 row_mirror row_mask:0xf bank_mask:0xf bound_ctrl:1
	v_add_f32_dpp v21, v19, v19 row_mirror row_mask:0xf bank_mask:0xf bound_ctrl:1
	v_mov_b32_e32 v20, v127
	v_pk_mul_f32 v[18:19], v[126:127], v[50:51]
	v_pk_fma_f32 v[2:3], v[44:45], v[20:21], v[2:3] op_sel_hi:[1,0,1]
	v_pk_fma_f32 v[0:1], v[42:43], v[20:21], v[0:1] op_sel_hi:[1,0,1]
	v_add_f32_e32 v18, v18, v21
	v_pk_mul_f32 v[20:21], v[22:23], v[0:1]
	v_pk_mul_f32 v[22:23], v[24:25], v[2:3]
	v_pk_mul_f32 v[2:3], v[12:13], v[2:3]
	v_sub_f32_e32 v18, v18, v19
	v_pk_fma_f32 v[12:13], v[32:33], v[38:39], v[22:23] op_sel_hi:[1,0,1]
	v_pk_fma_f32 v[0:1], v[10:11], v[0:1], v[2:3]
	v_pk_fma_f32 v[20:21], v[30:31], v[38:39], v[20:21] op_sel_hi:[1,0,1]
	v_pk_fma_f32 v[10:11], v[48:49], v[18:19], v[12:13] op_sel_hi:[1,0,1]
	v_add_f32_e32 v12, v0, v1
	v_pk_fma_f32 v[2:3], v[46:47], v[18:19], v[20:21] op_sel_hi:[1,0,1]
	v_pk_mul_f32 v[0:1], v[16:17], v[10:11]
	v_add_f32_dpp v20, v12, v12 quad_perm:[1,0,3,2] row_mask:0xf bank_mask:0xf bound_ctrl:1
	v_pk_mul_f32 v[12:13], v[80:81], v[10:11]
	v_pk_mul_f32 v[16:17], v[84:85], v[10:11]
	v_pk_fma_f32 v[0:1], v[14:15], v[2:3], v[0:1]
	v_pk_fma_f32 v[12:13], v[78:79], v[2:3], v[12:13]
	v_pk_mul_f32 v[18:19], v[62:63], v[2:3]
	v_pk_fma_f32 v[2:3], v[82:83], v[2:3], v[16:17]
	v_add_f32_e32 v0, v0, v1
	v_add_f32_e32 v1, v12, v13
	v_add_f32_e32 v2, v2, v3
	v_add_f32_dpp v0, v0, v0 quad_perm:[1,0,3,2] row_mask:0xf bank_mask:0xf bound_ctrl:1
	v_add_f32_dpp v1, v1, v1 quad_perm:[1,0,3,2] row_mask:0xf bank_mask:0xf bound_ctrl:1
	v_add_f32_dpp v2, v2, v2 quad_perm:[1,0,3,2] row_mask:0xf bank_mask:0xf bound_ctrl:1
	v_cndmask_b32_e32 v0, v0, v20, vcc
	v_add_f32_dpp v1, v1, v1 quad_perm:[2,3,0,1] row_mask:0xf bank_mask:0xf bound_ctrl:1
	v_add_f32_dpp v2, v2, v2 quad_perm:[2,3,0,1] row_mask:0xf bank_mask:0xf bound_ctrl:1
	v_add_f32_dpp v0, v0, v0 row_ror:2 row_mask:0xf bank_mask:0xf bound_ctrl:1
	v_add_f32_dpp v1, v1, v1 row_half_mirror row_mask:0xf bank_mask:0xf bound_ctrl:1
	v_pk_mul_f32 v[10:11], v[64:65], v[10:11]
	v_add_f32_dpp v2, v2, v2 row_half_mirror row_mask:0xf bank_mask:0xf bound_ctrl:1
	v_add_f32_dpp v0, v0, v0 row_ror:4 row_mask:0xf bank_mask:0xf bound_ctrl:1
	v_add_f32_dpp v41, v1, v1 row_mirror row_mask:0xf bank_mask:0xf bound_ctrl:1
	s_waitcnt lgkmcnt(12)
; template <int CTRL> __device__ __forceinline__ float dppf(float x) { return __builtin_bit_cast(float, __builtin_amdgcn_mov_dpp(__builtin_bit_cast(int, x), CTRL, 0xf, 0xf, true)); }
; __device__ __forceinline__ void scan_unit(const Params& p, int unit) {
;     ...
;             for (int pr = 0; pr < SC_TC / 2; ++pr) {
;                 const int sn = 2 * pr + 2;
;                 const f32x4 r1n = SC_LD(0, sn), w1n = SC_LD(1, sn), k1n = SC_LD(2, sn), q1n = SC_LD(3, sn), n1n = SC_LD(4, sn);
;                 const f32x4 r2n = SC_LD(0, sn + 1), w2n = SC_LD(1, sn + 1), k2n = SC_LD(2, sn + 1), g2n = SC_LD(3, sn + 1), n2n = SC_LD(4, sn + 1);
;                 const float v1n = buf[SC_VOFF + sn * 16 + rl], v2n = buf[SC_VOFF + (sn + 1) * 16 + rl];
;                 const f32x2 cfn = *(const f32x2*)(buf + SC_COFF + (pr + 1) * 2);
;                 __builtin_amdgcn_sched_barrier(0x7);
;                 float d1 = dot4(S, q1), e2 = dot4(S, g2);
;                 const f32x4 t1 = S * w1 + v1 * k1;
;                 reduce16x2(d1, e2);
;                 const float d2 = e2 + v1 * cf[0] - d1 * cf[1];
;                 const f32x4 S1 = t1 + d1 * n1;
;                 const f32x4 S2 = (S1 * w2 + v2 * k2) + d2 * n2;
;                 float y1 = dot4(S1, r1), y2 = dot4(S2, r2);
;                 y1 += dppf<0xB1>(y1); y2 += dppf<0xB1>(y2);
;                 float yz = odd_lane ? y2 : y1;
;                 yz += dppf<0x122>(yz); yz += dppf<0x124>(yz); yz += dppf<0x128>(yz);
;                 yb[(2 * pr) * 16 + yoff] = yz;
;                 S = S2;
;                 r1 = r1n; w1 = w1n; k1 = k1n; q1 = q1n; n1 = n1n; r2 = r2n; w2 = w2n; k2 = k2n; g2 = g2n; n2 = n2n; v1 = v1n; v2 = v2n; cf = cfn;
	v_mov_b32_e32 v40, v142
	v_pk_fma_f32 v[14:15], v[70:71], v[142:143], v[18:19] op_sel_hi:[1,0,1]
	v_pk_fma_f32 v[10:11], v[72:73], v[142:143], v[10:11] op_sel_hi:[1,0,1]
	v_add_f32_dpp v1, v2, v2 row_mirror row_mask:0xf bank_mask:0xf bound_ctrl:1
	v_add_f32_dpp v2, v0, v0 row_ror:8 row_mask:0xf bank_mask:0xf bound_ctrl:1
	v_mov_b32_e32 v0, v41
	v_pk_mul_f32 v[46:47], v[40:41], v[52:53]
	v_pk_fma_f32 v[48:49], v[88:89], v[0:1], v[10:11] op_sel_hi:[1,0,1]
	v_pk_fma_f32 v[50:51], v[86:87], v[0:1], v[14:15] op_sel_hi:[1,0,1]
	v_mov_b32_e32 v148, v143
	v_add_f32_e32 v46, v46, v1
	v_pk_mul_f32 v[52:53], v[66:67], v[50:51]
	v_pk_mul_f32 v[62:63], v[68:69], v[48:49]
	v_pk_mul_f32 v[48:49], v[56:57], v[48:49]
	v_sub_f32_e32 v46, v46, v47
	v_pk_fma_f32 v[56:57], v[76:77], v[148:149], v[62:63] op_sel_hi:[1,0,1]
	v_pk_fma_f32 v[52:53], v[74:75], v[148:149], v[52:53] op_sel_hi:[1,0,1]
	v_pk_fma_f32 v[48:49], v[54:55], v[50:51], v[48:49]
	v_pk_fma_f32 v[50:51], v[90:91], v[46:47], v[52:53] op_sel_hi:[1,0,1]
	v_pk_fma_f32 v[46:47], v[92:93], v[46:47], v[56:57] op_sel_hi:[1,0,1]
	v_add_f32_e32 v52, v48, v49
	v_pk_mul_f32 v[48:49], v[60:61], v[46:47]
	v_add_f32_dpp v60, v52, v52 quad_perm:[1,0,3,2] row_mask:0xf bank_mask:0xf bound_ctrl:1
	s_waitcnt lgkmcnt(5)
	ds_write_b32 v6, v2
	ds_read_b128 v[0:3], v8 offset:1536
	ds_read_b128 v[10:13], v8 offset:1792
	ds_read_b128 v[14:17], v8 offset:9728
	ds_read_b128 v[18:21], v8 offset:9984
	ds_read_b128 v[22:25], v8 offset:17920
	ds_read_b128 v[26:29], v8 offset:18176
	ds_read_b128 v[30:33], v8 offset:26112
	ds_read_b128 v[34:37], v8 offset:26368
	ds_read_b128 v[38:41], v8 offset:34304
	ds_read_b128 v[42:45], v8 offset:34560
	ds_read2_b32 v[86:87], v129 offset0:96 offset1:112
	ds_read_b64 v[88:89], v7 offset:43032
	v_pk_mul_f32 v[52:53], v[120:121], v[46:47]
	s_waitcnt lgkmcnt(15)
	v_pk_mul_f32 v[54:55], v[124:125], v[46:47]
	v_pk_fma_f32 v[48:49], v[58:59], v[50:51], v[48:49]
	v_pk_fma_f32 v[52:53], v[118:119], v[50:51], v[52:53]
	v_pk_mul_f32 v[56:57], v[102:103], v[50:51]
	v_pk_fma_f32 v[50:51], v[122:123], v[50:51], v[54:55]
	v_add_f32_e32 v48, v48, v49
	v_add_f32_e32 v49, v52, v53
	v_add_f32_e32 v50, v50, v51
	v_add_f32_dpp v48, v48, v48 quad_perm:[1,0,3,2] row_mask:0xf bank_mask:0xf bound_ctrl:1
	v_add_f32_dpp v49, v49, v49 quad_perm:[1,0,3,2] row_mask:0xf bank_mask:0xf bound_ctrl:1
	v_add_f32_dpp v50, v50, v50 quad_perm:[1,0,3,2] row_mask:0xf bank_mask:0xf bound_ctrl:1
	v_cndmask_b32_e32 v48, v48, v60, vcc
	v_add_f32_dpp v49, v49, v49 quad_perm:[2,3,0,1] row_mask:0xf bank_mask:0xf bound_ctrl:1
	v_add_f32_dpp v50, v50, v50 quad_perm:[2,3,0,1] row_mask:0xf bank_mask:0xf bound_ctrl:1
	v_add_f32_dpp v48, v48, v48 row_ror:2 row_mask:0xf bank_mask:0xf bound_ctrl:1
	v_add_f32_dpp v49, v49, v49 row_half_mirror row_mask:0xf bank_mask:0xf bound_ctrl:1
	v_pk_mul_f32 v[46:47], v[104:105], v[46:47]
	v_add_f32_dpp v50, v50, v50 row_half_mirror row_mask:0xf bank_mask:0xf bound_ctrl:1
	v_add_f32_dpp v48, v48, v48 row_ror:4 row_mask:0xf bank_mask:0xf bound_ctrl:1
	v_add_f32_dpp v151, v49, v49 row_mirror row_mask:0xf bank_mask:0xf bound_ctrl:1
	s_waitcnt lgkmcnt(14)
	v_mov_b32_e32 v150, v144
	v_pk_fma_f32 v[54:55], v[110:111], v[144:145], v[56:57] op_sel_hi:[1,0,1]
	v_pk_fma_f32 v[46:47], v[112:113], v[144:145], v[46:47] op_sel_hi:[1,0,1]
	v_add_f32_dpp v49, v50, v50 row_mirror row_mask:0xf bank_mask:0xf bound_ctrl:1
	v_add_f32_dpp v50, v48, v48 row_ror:8 row_mask:0xf bank_mask:0xf bound_ctrl:1
	v_mov_b32_e32 v48, v151
	s_waitcnt lgkmcnt(13)
	v_pk_mul_f32 v[92:93], v[150:151], v[146:147]
	v_pk_fma_f32 v[102:103], v[136:137], v[48:49], v[46:47] op_sel_hi:[1,0,1]
	v_pk_fma_f32 v[104:105], v[134:135], v[48:49], v[54:55] op_sel_hi:[1,0,1]
	v_mov_b32_e32 v152, v145
	v_add_f32_e32 v91, v92, v49
	v_pk_mul_f32 v[106:107], v[106:107], v[104:105]
	v_pk_mul_f32 v[108:109], v[108:109], v[102:103]
	v_sub_f32_e32 v92, v91, v93
	v_pk_mul_f32 v[96:97], v[96:97], v[102:103]
	v_pk_fma_f32 v[102:103], v[116:117], v[152:153], v[108:109] op_sel_hi:[1,0,1]
	v_pk_fma_f32 v[106:107], v[114:115], v[152:153], v[106:107] op_sel_hi:[1,0,1]
	v_pk_fma_f32 v[94:95], v[94:95], v[104:105], v[96:97]
	v_pk_fma_f32 v[96:97], v[138:139], v[92:93], v[106:107] op_sel_hi:[1,0,1]
	v_pk_fma_f32 v[92:93], v[140:141], v[92:93], v[102:103] op_sel_hi:[1,0,1]
	v_add_f32_e32 v91, v94, v95
	v_pk_mul_f32 v[94:95], v[100:101], v[92:93]
	s_waitcnt lgkmcnt(5)
	ds_write_b32 v6, v50 offset:128
	ds_read_b128 v[46:49], v8 offset:2048
	ds_read_b128 v[50:53], v8 offset:2304
	ds_read_b128 v[54:57], v8 offset:10240
	ds_read_b128 v[58:61], v8 offset:10496
	ds_read_b128 v[62:65], v8 offset:18432
	ds_read_b128 v[66:69], v8 offset:18688
	ds_read_b128 v[70:73], v8 offset:26624
	ds_read_b128 v[74:77], v8 offset:26880
	ds_read_b128 v[78:81], v8 offset:34816
	ds_read_b128 v[82:85], v8 offset:35072
	ds_read2_b32 v[112:113], v129 offset0:128 offset1:144
	ds_read_b64 v[118:119], v7 offset:43040
	v_pk_mul_f32 v[32:33], v[32:33], v[92:93]
	s_waitcnt lgkmcnt(15)
	v_pk_mul_f32 v[36:37], v[36:37], v[92:93]
	v_pk_mul_f32 v[16:17], v[16:17], v[92:93]
	v_pk_mul_f32 v[14:15], v[14:15], v[96:97]
	v_pk_fma_f32 v[92:93], v[98:99], v[96:97], v[94:95]
	v_pk_fma_f32 v[30:31], v[30:31], v[96:97], v[32:33]
	s_waitcnt lgkmcnt(14)
; template <int CTRL> __device__ __forceinline__ float dppf(float x) { return __builtin_bit_cast(float, __builtin_amdgcn_mov_dpp(__builtin_bit_cast(int, x), CTRL, 0xf, 0xf, true)); }
; __device__ __forceinline__ void scan_unit(const Params& p, int unit) {
;     ...
;             for (int pr = 0; pr < SC_TC / 2; ++pr) {
;                 const int sn = 2 * pr + 2;
;                 const f32x4 r1n = SC_LD(0, sn), w1n = SC_LD(1, sn), k1n = SC_LD(2, sn), q1n = SC_LD(3, sn), n1n = SC_LD(4, sn);
;                 const f32x4 r2n = SC_LD(0, sn + 1), w2n = SC_LD(1, sn + 1), k2n = SC_LD(2, sn + 1), g2n = SC_LD(3, sn + 1), n2n = SC_LD(4, sn + 1);
;                 const float v1n = buf[SC_VOFF + sn * 16 + rl], v2n = buf[SC_VOFF + (sn + 1) * 16 + rl];
;                 const f32x2 cfn = *(const f32x2*)(buf + SC_COFF + (pr + 1) * 2);
;                 __builtin_amdgcn_sched_barrier(0x7);
;                 float d1 = dot4(S, q1), e2 = dot4(S, g2);
;                 const f32x4 t1 = S * w1 + v1 * k1;
;                 reduce16x2(d1, e2);
;                 const float d2 = e2 + v1 * cf[0] - d1 * cf[1];
;                 const f32x4 S1 = t1 + d1 * n1;
;                 const f32x4 S2 = (S1 * w2 + v2 * k2) + d2 * n2;
;                 float y1 = dot4(S1, r1), y2 = dot4(S2, r2);
;                 y1 += dppf<0xB1>(y1); y2 += dppf<0xB1>(y2);
;                 float yz = odd_lane ? y2 : y1;
;                 yz += dppf<0x122>(yz); yz += dppf<0x124>(yz); yz += dppf<0x128>(yz);
;                 yb[(2 * pr) * 16 + yoff] = yz;
;                 S = S2;
;                 r1 = r1n; w1 = w1n; k1 = k1n; q1 = q1n; n1 = n1n; r2 = r2n; w2 = w2n; k2 = k2n; g2 = g2n; n2 = n2n; v1 = v1n; v2 = v2n; cf = cfn;
	v_pk_fma_f32 v[14:15], v[22:23], v[86:87], v[14:15] op_sel_hi:[1,0,1]
	v_add_f32_e32 v22, v92, v93
	v_add_f32_e32 v23, v30, v31
	v_add_f32_dpp v91, v91, v91 quad_perm:[1,0,3,2] row_mask:0xf bank_mask:0xf bound_ctrl:1
	v_pk_fma_f32 v[32:33], v[34:35], v[96:97], v[36:37]
	v_add_f32_dpp v22, v22, v22 quad_perm:[1,0,3,2] row_mask:0xf bank_mask:0xf bound_ctrl:1
	v_add_f32_dpp v23, v23, v23 quad_perm:[1,0,3,2] row_mask:0xf bank_mask:0xf bound_ctrl:1
	v_pk_fma_f32 v[16:17], v[24:25], v[86:87], v[16:17] op_sel_hi:[1,0,1]
	v_add_f32_e32 v24, v32, v33
	v_cndmask_b32_e32 v22, v22, v91, vcc
	v_add_f32_dpp v23, v23, v23 quad_perm:[2,3,0,1] row_mask:0xf bank_mask:0xf bound_ctrl:1
	v_add_f32_dpp v24, v24, v24 quad_perm:[1,0,3,2] row_mask:0xf bank_mask:0xf bound_ctrl:1
	v_add_f32_dpp v22, v22, v22 row_ror:2 row_mask:0xf bank_mask:0xf bound_ctrl:1
	v_add_f32_dpp v23, v23, v23 row_half_mirror row_mask:0xf bank_mask:0xf bound_ctrl:1
	v_add_f32_dpp v24, v24, v24 quad_perm:[2,3,0,1] row_mask:0xf bank_mask:0xf bound_ctrl:1
	v_add_f32_dpp v22, v22, v22 row_ror:4 row_mask:0xf bank_mask:0xf bound_ctrl:1
	v_add_f32_dpp v91, v23, v23 row_mirror row_mask:0xf bank_mask:0xf bound_ctrl:1
	v_mov_b32_e32 v90, v86
	v_add_f32_dpp v24, v24, v24 row_half_mirror row_mask:0xf bank_mask:0xf bound_ctrl:1
	v_add_f32_dpp v23, v22, v22 row_ror:8 row_mask:0xf bank_mask:0xf bound_ctrl:1
	v_mov_b32_e32 v22, v91
	v_add_f32_dpp v107, v24, v24 row_mirror row_mask:0xf bank_mask:0xf bound_ctrl:1
	s_waitcnt lgkmcnt(13)
	v_pk_mul_f32 v[120:121], v[90:91], v[88:89]
	v_pk_fma_f32 v[122:123], v[40:41], v[22:23], v[16:17] op_sel_hi:[1,0,1]
	v_pk_fma_f32 v[124:125], v[38:39], v[22:23], v[14:15] op_sel_hi:[1,0,1]
	v_mov_b32_e32 v110, v87
	v_add_f32_e32 v107, v120, v107
	v_pk_mul_f32 v[18:19], v[18:19], v[124:125]
	v_pk_mul_f32 v[20:21], v[20:21], v[122:123]
	v_pk_mul_f32 v[2:3], v[2:3], v[122:123]
	v_sub_f32_e32 v120, v107, v121
	v_pk_fma_f32 v[20:21], v[28:29], v[110:111], v[20:21] op_sel_hi:[1,0,1]
	v_pk_fma_f32 v[18:19], v[26:27], v[110:111], v[18:19] op_sel_hi:[1,0,1]
	v_pk_fma_f32 v[0:1], v[0:1], v[124:125], v[2:3]
	v_pk_fma_f32 v[2:3], v[42:43], v[120:121], v[18:19] op_sel_hi:[1,0,1]
	v_pk_fma_f32 v[18:19], v[44:45], v[120:121], v[20:21] op_sel_hi:[1,0,1]
	v_add_f32_e32 v20, v0, v1
	v_pk_mul_f32 v[0:1], v[12:13], v[18:19]
	s_waitcnt lgkmcnt(5)
	v_pk_mul_f32 v[12:13], v[72:73], v[18:19]
	v_add_f32_dpp v28, v20, v20 quad_perm:[1,0,3,2] row_mask:0xf bank_mask:0xf bound_ctrl:1
	s_waitcnt lgkmcnt(4)
	ds_write_b32 v6, v23 offset:256
	ds_read_b64 v[114:115], v7 offset:43048
	ds_read_b64 v[116:117], v7 offset:43056
	ds_read_b128 v[14:17], v8 offset:2560
	ds_read_b128 v[22:25], v8 offset:2816
	ds_read_b128 v[30:33], v8 offset:10752
	ds_read_b128 v[34:37], v8 offset:11008
	ds_read_b128 v[38:41], v8 offset:18944
	ds_read_b128 v[86:89], v8 offset:19200
	ds_read_b128 v[90:93], v8 offset:27136
	ds_read_b128 v[94:97], v8 offset:27392
	ds_read_b128 v[98:101], v8 offset:35328
	ds_read_b128 v[102:105], v8 offset:35584
	ds_read2_b32 v[126:127], v129 offset0:160 offset1:176
	v_pk_mul_f32 v[20:21], v[76:77], v[18:19]
	v_pk_fma_f32 v[0:1], v[10:11], v[2:3], v[0:1]
	v_pk_fma_f32 v[10:11], v[70:71], v[2:3], v[12:13]
	v_pk_mul_f32 v[26:27], v[54:55], v[2:3]
	v_pk_fma_f32 v[2:3], v[74:75], v[2:3], v[20:21]
	v_add_f32_e32 v0, v0, v1
	v_add_f32_e32 v1, v10, v11
	v_add_f32_e32 v2, v2, v3
	v_add_f32_dpp v0, v0, v0 quad_perm:[1,0,3,2] row_mask:0xf bank_mask:0xf bound_ctrl:1
	v_add_f32_dpp v1, v1, v1 quad_perm:[1,0,3,2] row_mask:0xf bank_mask:0xf bound_ctrl:1
	v_add_f32_dpp v2, v2, v2 quad_perm:[1,0,3,2] row_mask:0xf bank_mask:0xf bound_ctrl:1
	v_cndmask_b32_e32 v0, v0, v28, vcc
	v_add_f32_dpp v1, v1, v1 quad_perm:[2,3,0,1] row_mask:0xf bank_mask:0xf bound_ctrl:1
	v_add_f32_dpp v2, v2, v2 quad_perm:[2,3,0,1] row_mask:0xf bank_mask:0xf bound_ctrl:1
	v_add_f32_dpp v0, v0, v0 row_ror:2 row_mask:0xf bank_mask:0xf bound_ctrl:1
	v_add_f32_dpp v1, v1, v1 row_half_mirror row_mask:0xf bank_mask:0xf bound_ctrl:1
	v_pk_mul_f32 v[18:19], v[56:57], v[18:19]
	v_add_f32_dpp v2, v2, v2 row_half_mirror row_mask:0xf bank_mask:0xf bound_ctrl:1
	v_add_f32_dpp v0, v0, v0 row_ror:4 row_mask:0xf bank_mask:0xf bound_ctrl:1
	v_add_f32_dpp v107, v1, v1 row_mirror row_mask:0xf bank_mask:0xf bound_ctrl:1
	s_waitcnt lgkmcnt(15)
	v_mov_b32_e32 v106, v112
	v_pk_fma_f32 v[12:13], v[62:63], v[112:113], v[26:27] op_sel_hi:[1,0,1]
	v_pk_fma_f32 v[18:19], v[64:65], v[112:113], v[18:19] op_sel_hi:[1,0,1]
	v_add_f32_dpp v1, v2, v2 row_mirror row_mask:0xf bank_mask:0xf bound_ctrl:1
	v_add_f32_dpp v2, v0, v0 row_ror:8 row_mask:0xf bank_mask:0xf bound_ctrl:1
	v_mov_b32_e32 v0, v107
	s_waitcnt lgkmcnt(14)
	v_pk_mul_f32 v[118:119], v[106:107], v[118:119]
	v_pk_fma_f32 v[106:107], v[80:81], v[0:1], v[18:19] op_sel_hi:[1,0,1]
	v_pk_fma_f32 v[120:121], v[78:79], v[0:1], v[12:13] op_sel_hi:[1,0,1]
	v_mov_b32_e32 v108, v113
	v_add_f32_e32 v109, v118, v1
	v_pk_mul_f32 v[58:59], v[58:59], v[120:121]
	v_pk_mul_f32 v[60:61], v[60:61], v[106:107]
	v_sub_f32_e32 v118, v109, v119
	v_pk_mul_f32 v[48:49], v[48:49], v[106:107]
	v_pk_fma_f32 v[60:61], v[68:69], v[108:109], v[60:61] op_sel_hi:[1,0,1]
	v_pk_fma_f32 v[58:59], v[66:67], v[108:109], v[58:59] op_sel_hi:[1,0,1]
	v_pk_fma_f32 v[46:47], v[46:47], v[120:121], v[48:49]
	v_pk_fma_f32 v[48:49], v[82:83], v[118:119], v[58:59] op_sel_hi:[1,0,1]
	v_pk_fma_f32 v[58:59], v[84:85], v[118:119], v[60:61] op_sel_hi:[1,0,1]
	v_add_f32_e32 v60, v46, v47
	v_pk_mul_f32 v[46:47], v[52:53], v[58:59]
	s_waitcnt lgkmcnt(4)
; template <int CTRL> __device__ __forceinline__ float dppf(float x) { return __builtin_bit_cast(float, __builtin_amdgcn_mov_dpp(__builtin_bit_cast(int, x), CTRL, 0xf, 0xf, true)); }
; __device__ __forceinline__ void scan_unit(const Params& p, int unit) {
;     ...
;             for (int pr = 0; pr < SC_TC / 2; ++pr) {
;                 const int sn = 2 * pr + 2;
;                 const f32x4 r1n = SC_LD(0, sn), w1n = SC_LD(1, sn), k1n = SC_LD(2, sn), q1n = SC_LD(3, sn), n1n = SC_LD(4, sn);
;                 const f32x4 r2n = SC_LD(0, sn + 1), w2n = SC_LD(1, sn + 1), k2n = SC_LD(2, sn + 1), g2n = SC_LD(3, sn + 1), n2n = SC_LD(4, sn + 1);
;                 const float v1n = buf[SC_VOFF + sn * 16 + rl], v2n = buf[SC_VOFF + (sn + 1) * 16 + rl];
;                 const f32x2 cfn = *(const f32x2*)(buf + SC_COFF + (pr + 1) * 2);
;                 __builtin_amdgcn_sched_barrier(0x7);
;                 float d1 = dot4(S, q1), e2 = dot4(S, g2);
;                 const f32x4 t1 = S * w1 + v1 * k1;
;                 reduce16x2(d1, e2);
;                 const float d2 = e2 + v1 * cf[0] - d1 * cf[1];
;                 const f32x4 S1 = t1 + d1 * n1;
;                 const f32x4 S2 = (S1 * w2 + v2 * k2) + d2 * n2;
;                 float y1 = dot4(S1, r1), y2 = dot4(S2, r2);
;                 y1 += dppf<0xB1>(y1); y2 += dppf<0xB1>(y2);
;                 float yz = odd_lane ? y2 : y1;
;                 yz += dppf<0x122>(yz); yz += dppf<0x124>(yz); yz += dppf<0x128>(yz);
;                 yb[(2 * pr) * 16 + yoff] = yz;
;                 S = S2;
;                 r1 = r1n; w1 = w1n; k1 = k1n; q1 = q1n; n1 = n1n; r2 = r2n; w2 = w2n; k2 = k2n; g2 = g2n; n2 = n2n; v1 = v1n; v2 = v2n; cf = cfn;
	ds_write_b32 v6, v2 offset:384
	ds_read_b128 v[0:3], v8 offset:3072
	ds_read_b128 v[10:13], v8 offset:3328
	ds_read_b128 v[18:21], v8 offset:11264
	ds_read_b128 v[26:29], v8 offset:11520
	ds_read_b128 v[42:45], v8 offset:19456
	ds_read_b128 v[54:57], v8 offset:19712
	ds_read_b128 v[62:65], v8 offset:27648
	ds_read_b128 v[70:73], v8 offset:27904
	ds_read_b128 v[74:77], v8 offset:35840
	ds_read_b128 v[78:81], v8 offset:36096
	ds_read2_b32 v[122:123], v129 offset0:192 offset1:208
	v_pk_mul_f32 v[52:53], v[92:93], v[58:59]
	v_add_f32_dpp v66, v60, v60 quad_perm:[1,0,3,2] row_mask:0xf bank_mask:0xf bound_ctrl:1
	s_waitcnt lgkmcnt(15)
	v_pk_mul_f32 v[60:61], v[96:97], v[58:59]
	v_pk_mul_f32 v[30:31], v[30:31], v[48:49]
	v_pk_fma_f32 v[46:47], v[50:51], v[48:49], v[46:47]
	v_pk_fma_f32 v[50:51], v[90:91], v[48:49], v[52:53]
	v_pk_mul_f32 v[32:33], v[32:33], v[58:59]
	v_pk_fma_f32 v[48:49], v[94:95], v[48:49], v[60:61]
	s_waitcnt lgkmcnt(12)
	v_pk_fma_f32 v[30:31], v[38:39], v[126:127], v[30:31] op_sel_hi:[1,0,1]
	v_add_f32_e32 v38, v46, v47
	v_add_f32_e32 v39, v50, v51
	v_pk_fma_f32 v[32:33], v[40:41], v[126:127], v[32:33] op_sel_hi:[1,0,1]
	v_add_f32_e32 v40, v48, v49
	v_add_f32_dpp v38, v38, v38 quad_perm:[1,0,3,2] row_mask:0xf bank_mask:0xf bound_ctrl:1
	v_add_f32_dpp v39, v39, v39 quad_perm:[1,0,3,2] row_mask:0xf bank_mask:0xf bound_ctrl:1
	v_add_f32_dpp v40, v40, v40 quad_perm:[1,0,3,2] row_mask:0xf bank_mask:0xf bound_ctrl:1
	v_cndmask_b32_e32 v38, v38, v66, vcc
	v_add_f32_dpp v39, v39, v39 quad_perm:[2,3,0,1] row_mask:0xf bank_mask:0xf bound_ctrl:1
	v_add_f32_dpp v40, v40, v40 quad_perm:[2,3,0,1] row_mask:0xf bank_mask:0xf bound_ctrl:1
	v_add_f32_dpp v38, v38, v38 row_ror:2 row_mask:0xf bank_mask:0xf bound_ctrl:1
	v_add_f32_dpp v39, v39, v39 row_half_mirror row_mask:0xf bank_mask:0xf bound_ctrl:1
	v_add_f32_dpp v40, v40, v40 row_half_mirror row_mask:0xf bank_mask:0xf bound_ctrl:1
	v_add_f32_dpp v38, v38, v38 row_ror:4 row_mask:0xf bank_mask:0xf bound_ctrl:1
	v_add_f32_dpp v111, v39, v39 row_mirror row_mask:0xf bank_mask:0xf bound_ctrl:1
	v_mov_b32_e32 v110, v126
	v_add_f32_dpp v39, v40, v40 row_mirror row_mask:0xf bank_mask:0xf bound_ctrl:1
	v_add_f32_dpp v40, v38, v38 row_ror:8 row_mask:0xf bank_mask:0xf bound_ctrl:1
	v_mov_b32_e32 v38, v111
	v_pk_mul_f32 v[114:115], v[110:111], v[114:115]
	v_pk_fma_f32 v[110:111], v[100:101], v[38:39], v[32:33] op_sel_hi:[1,0,1]
	v_pk_fma_f32 v[118:119], v[98:99], v[38:39], v[30:31] op_sel_hi:[1,0,1]
	v_mov_b32_e32 v112, v127
	v_add_f32_e32 v107, v114, v39
	v_pk_mul_f32 v[34:35], v[34:35], v[118:119]
	v_pk_mul_f32 v[36:37], v[36:37], v[110:111]
	v_sub_f32_e32 v114, v107, v115
	v_pk_mul_f32 v[16:17], v[16:17], v[110:111]
	v_pk_fma_f32 v[36:37], v[88:89], v[112:113], v[36:37] op_sel_hi:[1,0,1]
	v_pk_fma_f32 v[34:35], v[86:87], v[112:113], v[34:35] op_sel_hi:[1,0,1]
	v_pk_fma_f32 v[14:15], v[14:15], v[118:119], v[16:17]
	v_pk_fma_f32 v[16:17], v[102:103], v[114:115], v[34:35] op_sel_hi:[1,0,1]
	v_pk_fma_f32 v[34:35], v[104:105], v[114:115], v[36:37] op_sel_hi:[1,0,1]
	v_add_f32_e32 v36, v14, v15
	v_pk_mul_f32 v[14:15], v[24:25], v[34:35]
	s_waitcnt lgkmcnt(4)
	ds_write_b32 v6, v40 offset:512
	ds_read_b128 v[30:33], v8 offset:3584
	ds_read_b128 v[38:41], v8 offset:3840
	ds_read_b128 v[46:49], v8 offset:11776
	ds_read_b128 v[50:53], v8 offset:12032
	ds_read_b128 v[58:61], v8 offset:19968
	ds_read_b128 v[66:69], v8 offset:20224
	ds_read_b128 v[82:85], v8 offset:28160
	ds_read_b128 v[90:93], v8 offset:28416
	ds_read_b128 v[94:97], v8 offset:36352
	ds_read_b128 v[98:101], v8 offset:36608
	ds_read2_b32 v[120:121], v129 offset0:224 offset1:240
	ds_read_b64 v[124:125], v7 offset:43064
	v_pk_mul_f32 v[24:25], v[64:65], v[34:35]
	v_add_f32_dpp v86, v36, v36 quad_perm:[1,0,3,2] row_mask:0xf bank_mask:0xf bound_ctrl:1
	s_waitcnt lgkmcnt(15)
	v_pk_mul_f32 v[36:37], v[72:73], v[34:35]
	v_pk_fma_f32 v[14:15], v[22:23], v[16:17], v[14:15]
	v_pk_fma_f32 v[22:23], v[62:63], v[16:17], v[24:25]
	v_pk_mul_f32 v[18:19], v[18:19], v[16:17]
	v_pk_fma_f32 v[16:17], v[70:71], v[16:17], v[36:37]
	v_add_f32_e32 v14, v14, v15
	v_add_f32_e32 v15, v22, v23
	v_add_f32_e32 v16, v16, v17
	v_add_f32_dpp v14, v14, v14 quad_perm:[1,0,3,2] row_mask:0xf bank_mask:0xf bound_ctrl:1
	v_add_f32_dpp v15, v15, v15 quad_perm:[1,0,3,2] row_mask:0xf bank_mask:0xf bound_ctrl:1
	v_add_f32_dpp v16, v16, v16 quad_perm:[1,0,3,2] row_mask:0xf bank_mask:0xf bound_ctrl:1
	v_cndmask_b32_e32 v14, v14, v86, vcc
	v_add_f32_dpp v15, v15, v15 quad_perm:[2,3,0,1] row_mask:0xf bank_mask:0xf bound_ctrl:1
	v_add_f32_dpp v16, v16, v16 quad_perm:[2,3,0,1] row_mask:0xf bank_mask:0xf bound_ctrl:1
	v_add_f32_dpp v14, v14, v14 row_ror:2 row_mask:0xf bank_mask:0xf bound_ctrl:1
	v_add_f32_dpp v15, v15, v15 row_half_mirror row_mask:0xf bank_mask:0xf bound_ctrl:1
	v_pk_mul_f32 v[20:21], v[20:21], v[34:35]
	v_add_f32_dpp v16, v16, v16 row_half_mirror row_mask:0xf bank_mask:0xf bound_ctrl:1
	v_add_f32_dpp v14, v14, v14 row_ror:4 row_mask:0xf bank_mask:0xf bound_ctrl:1
	v_add_f32_dpp v107, v15, v15 row_mirror row_mask:0xf bank_mask:0xf bound_ctrl:1
	s_waitcnt lgkmcnt(13)
; template <int CTRL> __device__ __forceinline__ float dppf(float x) { return __builtin_bit_cast(float, __builtin_amdgcn_mov_dpp(__builtin_bit_cast(int, x), CTRL, 0xf, 0xf, true)); }
; __device__ __forceinline__ void scan_unit(const Params& p, int unit) {
;     ...
;             for (int pr = 0; pr < SC_TC / 2; ++pr) {
;                 const int sn = 2 * pr + 2;
;                 const f32x4 r1n = SC_LD(0, sn), w1n = SC_LD(1, sn), k1n = SC_LD(2, sn), q1n = SC_LD(3, sn), n1n = SC_LD(4, sn);
;                 const f32x4 r2n = SC_LD(0, sn + 1), w2n = SC_LD(1, sn + 1), k2n = SC_LD(2, sn + 1), g2n = SC_LD(3, sn + 1), n2n = SC_LD(4, sn + 1);
;                 const float v1n = buf[SC_VOFF + sn * 16 + rl], v2n = buf[SC_VOFF + (sn + 1) * 16 + rl];
;                 const f32x2 cfn = *(const f32x2*)(buf + SC_COFF + (pr + 1) * 2);
;                 __builtin_amdgcn_sched_barrier(0x7);
;                 float d1 = dot4(S, q1), e2 = dot4(S, g2);
;                 const f32x4 t1 = S * w1 + v1 * k1;
;                 reduce16x2(d1, e2);
;                 const float d2 = e2 + v1 * cf[0] - d1 * cf[1];
;                 const f32x4 S1 = t1 + d1 * n1;
;                 const f32x4 S2 = (S1 * w2 + v2 * k2) + d2 * n2;
;                 float y1 = dot4(S1, r1), y2 = dot4(S2, r2);
;                 y1 += dppf<0xB1>(y1); y2 += dppf<0xB1>(y2);
;                 float yz = odd_lane ? y2 : y1;
;                 yz += dppf<0x122>(yz); yz += dppf<0x124>(yz); yz += dppf<0x128>(yz);
;                 yb[(2 * pr) * 16 + yoff] = yz;
;                 S = S2;
;                 r1 = r1n; w1 = w1n; k1 = k1n; q1 = q1n; n1 = n1n; r2 = r2n; w2 = w2n; k2 = k2n; g2 = g2n; n2 = n2n; v1 = v1n; v2 = v2n; cf = cfn;
	v_mov_b32_e32 v106, v122
	v_pk_fma_f32 v[18:19], v[42:43], v[122:123], v[18:19] op_sel_hi:[1,0,1]
	v_pk_fma_f32 v[20:21], v[44:45], v[122:123], v[20:21] op_sel_hi:[1,0,1]
	v_add_f32_dpp v15, v16, v16 row_mirror row_mask:0xf bank_mask:0xf bound_ctrl:1
	v_add_f32_dpp v16, v14, v14 row_ror:8 row_mask:0xf bank_mask:0xf bound_ctrl:1
	v_mov_b32_e32 v14, v107
	v_pk_mul_f32 v[114:115], v[106:107], v[116:117]
	v_pk_fma_f32 v[106:107], v[76:77], v[14:15], v[20:21] op_sel_hi:[1,0,1]
	v_pk_fma_f32 v[116:117], v[74:75], v[14:15], v[18:19] op_sel_hi:[1,0,1]
	v_mov_b32_e32 v108, v123
	v_add_f32_e32 v109, v114, v15
	v_pk_mul_f32 v[26:27], v[26:27], v[116:117]
	v_pk_mul_f32 v[28:29], v[28:29], v[106:107]
	v_sub_f32_e32 v114, v109, v115
	v_pk_mul_f32 v[2:3], v[2:3], v[106:107]
	v_pk_fma_f32 v[28:29], v[56:57], v[108:109], v[28:29] op_sel_hi:[1,0,1]
	v_pk_fma_f32 v[26:27], v[54:55], v[108:109], v[26:27] op_sel_hi:[1,0,1]
	v_pk_fma_f32 v[0:1], v[0:1], v[116:117], v[2:3]
	v_pk_fma_f32 v[2:3], v[78:79], v[114:115], v[26:27] op_sel_hi:[1,0,1]
	v_pk_fma_f32 v[26:27], v[80:81], v[114:115], v[28:29] op_sel_hi:[1,0,1]
	v_add_f32_e32 v28, v0, v1
	v_pk_mul_f32 v[0:1], v[12:13], v[26:27]
	s_waitcnt lgkmcnt(5)
	ds_write_b32 v6, v16 offset:640
	v_add_u32_e32 v9, 0xa400, v9
	ds_read_b128 v[14:17], v8 offset:4096
	ds_read_b128 v[18:21], v8 offset:4352
	ds_read_b128 v[22:25], v8 offset:12288
	ds_read_b128 v[34:37], v8 offset:12544
	ds_read_b128 v[42:45], v8 offset:20480
	ds_read_b128 v[62:65], v8 offset:20736
	ds_read_b128 v[70:73], v8 offset:28672
	ds_read_b128 v[74:77], v8 offset:28928
	ds_read_b128 v[86:89], v8 offset:36864
	ds_read_b128 v[102:105], v8 offset:37120
	ds_read2_b32 v[118:119], v9 offset1:16
	ds_read_b64 v[122:123], v7 offset:43072
	v_pk_mul_f32 v[12:13], v[84:85], v[26:27]
	v_pk_fma_f32 v[0:1], v[10:11], v[2:3], v[0:1]
	v_pk_fma_f32 v[10:11], v[82:83], v[2:3], v[12:13]
	v_add_f32_dpp v54, v28, v28 quad_perm:[1,0,3,2] row_mask:0xf bank_mask:0xf bound_ctrl:1
	s_waitcnt lgkmcnt(15)
	v_pk_mul_f32 v[28:29], v[92:93], v[26:27]
	v_add_f32_e32 v0, v0, v1
	v_add_f32_e32 v1, v10, v11
	v_pk_mul_f32 v[46:47], v[46:47], v[2:3]
	v_pk_fma_f32 v[2:3], v[90:91], v[2:3], v[28:29]
	v_add_f32_dpp v0, v0, v0 quad_perm:[1,0,3,2] row_mask:0xf bank_mask:0xf bound_ctrl:1
	v_add_f32_dpp v1, v1, v1 quad_perm:[1,0,3,2] row_mask:0xf bank_mask:0xf bound_ctrl:1
	v_add_f32_e32 v2, v2, v3
	v_cndmask_b32_e32 v0, v0, v54, vcc
	v_add_f32_dpp v1, v1, v1 quad_perm:[2,3,0,1] row_mask:0xf bank_mask:0xf bound_ctrl:1
	v_add_f32_dpp v2, v2, v2 quad_perm:[1,0,3,2] row_mask:0xf bank_mask:0xf bound_ctrl:1
	v_add_f32_dpp v0, v0, v0 row_ror:2 row_mask:0xf bank_mask:0xf bound_ctrl:1
	v_add_f32_dpp v1, v1, v1 row_half_mirror row_mask:0xf bank_mask:0xf bound_ctrl:1
	v_pk_mul_f32 v[26:27], v[48:49], v[26:27]
	v_add_f32_dpp v2, v2, v2 quad_perm:[2,3,0,1] row_mask:0xf bank_mask:0xf bound_ctrl:1
	v_add_f32_dpp v0, v0, v0 row_ror:4 row_mask:0xf bank_mask:0xf bound_ctrl:1
	v_add_f32_dpp v111, v1, v1 row_mirror row_mask:0xf bank_mask:0xf bound_ctrl:1
	s_waitcnt lgkmcnt(14)
	v_mov_b32_e32 v110, v120
	v_pk_fma_f32 v[12:13], v[58:59], v[120:121], v[46:47] op_sel_hi:[1,0,1]
	v_pk_fma_f32 v[26:27], v[60:61], v[120:121], v[26:27] op_sel_hi:[1,0,1]
	v_add_f32_dpp v2, v2, v2 row_half_mirror row_mask:0xf bank_mask:0xf bound_ctrl:1
	v_add_f32_dpp v1, v0, v0 row_ror:8 row_mask:0xf bank_mask:0xf bound_ctrl:1
	v_mov_b32_e32 v0, v111
	v_mov_b32_e32 v112, v121
	v_add_f32_dpp v107, v2, v2 row_mirror row_mask:0xf bank_mask:0xf bound_ctrl:1
	s_waitcnt lgkmcnt(13)
	v_pk_mul_f32 v[110:111], v[110:111], v[124:125]
	v_pk_fma_f32 v[120:121], v[96:97], v[0:1], v[26:27] op_sel_hi:[1,0,1]
	v_pk_fma_f32 v[124:125], v[94:95], v[0:1], v[12:13] op_sel_hi:[1,0,1]
	v_add_f32_e32 v107, v110, v107
	v_pk_mul_f32 v[50:51], v[50:51], v[124:125]
	v_pk_mul_f32 v[52:53], v[52:53], v[120:121]
	v_pk_mul_f32 v[32:33], v[32:33], v[120:121]
	v_sub_f32_e32 v110, v107, v111
	v_pk_fma_f32 v[52:53], v[68:69], v[112:113], v[52:53] op_sel_hi:[1,0,1]
	v_pk_fma_f32 v[50:51], v[66:67], v[112:113], v[50:51] op_sel_hi:[1,0,1]
	v_pk_fma_f32 v[30:31], v[30:31], v[124:125], v[32:33]
	v_pk_fma_f32 v[32:33], v[98:99], v[110:111], v[50:51] op_sel_hi:[1,0,1]
	v_pk_fma_f32 v[50:51], v[100:101], v[110:111], v[52:53] op_sel_hi:[1,0,1]
	v_add_f32_e32 v52, v30, v31
	v_pk_mul_f32 v[30:31], v[40:41], v[50:51]
	s_waitcnt lgkmcnt(5)
	v_pk_mul_f32 v[40:41], v[72:73], v[50:51]
	v_add_f32_dpp v66, v52, v52 quad_perm:[1,0,3,2] row_mask:0xf bank_mask:0xf bound_ctrl:1
	s_waitcnt lgkmcnt(4)
	ds_write_b32 v6, v1 offset:768
	ds_read_b64 v[114:115], v7 offset:43080
	ds_read_b64 v[116:117], v7 offset:43088
	ds_read_b128 v[0:3], v8 offset:4608
	ds_read_b128 v[10:13], v8 offset:4864
	ds_read_b128 v[26:29], v8 offset:12800
	ds_read_b128 v[46:49], v8 offset:13056
	ds_read_b128 v[54:57], v8 offset:20992
	ds_read_b128 v[58:61], v8 offset:21248
	ds_read_b128 v[78:81], v8 offset:29184
	ds_read_b128 v[82:85], v8 offset:29440
	ds_read_b128 v[90:93], v8 offset:37376
	ds_read_b128 v[94:97], v8 offset:37632
	ds_read2_b32 v[126:127], v9 offset0:32 offset1:48
	v_pk_mul_f32 v[52:53], v[76:77], v[50:51]
	v_pk_fma_f32 v[30:31], v[38:39], v[32:33], v[30:31]
	v_pk_fma_f32 v[38:39], v[70:71], v[32:33], v[40:41]
	v_pk_mul_f32 v[22:23], v[22:23], v[32:33]
	v_pk_fma_f32 v[32:33], v[74:75], v[32:33], v[52:53]
	v_add_f32_e32 v30, v30, v31
	v_add_f32_e32 v31, v38, v39
	v_add_f32_e32 v32, v32, v33
	v_add_f32_dpp v30, v30, v30 quad_perm:[1,0,3,2] row_mask:0xf bank_mask:0xf bound_ctrl:1
	v_add_f32_dpp v31, v31, v31 quad_perm:[1,0,3,2] row_mask:0xf bank_mask:0xf bound_ctrl:1
	v_add_f32_dpp v32, v32, v32 quad_perm:[1,0,3,2] row_mask:0xf bank_mask:0xf bound_ctrl:1
	v_cndmask_b32_e32 v30, v30, v66, vcc
	v_add_f32_dpp v31, v31, v31 quad_perm:[2,3,0,1] row_mask:0xf bank_mask:0xf bound_ctrl:1
	v_add_f32_dpp v32, v32, v32 quad_perm:[2,3,0,1] row_mask:0xf bank_mask:0xf bound_ctrl:1
	v_add_f32_dpp v30, v30, v30 row_ror:2 row_mask:0xf bank_mask:0xf bound_ctrl:1
	v_add_f32_dpp v31, v31, v31 row_half_mirror row_mask:0xf bank_mask:0xf bound_ctrl:1
	v_pk_mul_f32 v[24:25], v[24:25], v[50:51]
	v_add_f32_dpp v32, v32, v32 row_half_mirror row_mask:0xf bank_mask:0xf bound_ctrl:1
	v_add_f32_dpp v30, v30, v30 row_ror:4 row_mask:0xf bank_mask:0xf bound_ctrl:1
	v_add_f32_dpp v107, v31, v31 row_mirror row_mask:0xf bank_mask:0xf bound_ctrl:1
	s_waitcnt lgkmcnt(15)
; template <int CTRL> __device__ __forceinline__ float dppf(float x) { return __builtin_bit_cast(float, __builtin_amdgcn_mov_dpp(__builtin_bit_cast(int, x), CTRL, 0xf, 0xf, true)); }
; __device__ __forceinline__ void scan_unit(const Params& p, int unit) {
;     ...
;             for (int pr = 0; pr < SC_TC / 2; ++pr) {
;                 const int sn = 2 * pr + 2;
;                 const f32x4 r1n = SC_LD(0, sn), w1n = SC_LD(1, sn), k1n = SC_LD(2, sn), q1n = SC_LD(3, sn), n1n = SC_LD(4, sn);
;                 const f32x4 r2n = SC_LD(0, sn + 1), w2n = SC_LD(1, sn + 1), k2n = SC_LD(2, sn + 1), g2n = SC_LD(3, sn + 1), n2n = SC_LD(4, sn + 1);
;                 const float v1n = buf[SC_VOFF + sn * 16 + rl], v2n = buf[SC_VOFF + (sn + 1) * 16 + rl];
;                 const f32x2 cfn = *(const f32x2*)(buf + SC_COFF + (pr + 1) * 2);
;                 __builtin_amdgcn_sched_barrier(0x7);
;                 float d1 = dot4(S, q1), e2 = dot4(S, g2);
;                 const f32x4 t1 = S * w1 + v1 * k1;
;                 reduce16x2(d1, e2);
;                 const float d2 = e2 + v1 * cf[0] - d1 * cf[1];
;                 const f32x4 S1 = t1 + d1 * n1;
;                 const f32x4 S2 = (S1 * w2 + v2 * k2) + d2 * n2;
;                 float y1 = dot4(S1, r1), y2 = dot4(S2, r2);
;                 y1 += dppf<0xB1>(y1); y2 += dppf<0xB1>(y2);
;                 float yz = odd_lane ? y2 : y1;
;                 yz += dppf<0x122>(yz); yz += dppf<0x124>(yz); yz += dppf<0x128>(yz);
;                 yb[(2 * pr) * 16 + yoff] = yz;
;                 S = S2;
;                 r1 = r1n; w1 = w1n; k1 = k1n; q1 = q1n; n1 = n1n; r2 = r2n; w2 = w2n; k2 = k2n; g2 = g2n; n2 = n2n; v1 = v1n; v2 = v2n; cf = cfn;
	v_mov_b32_e32 v106, v118
	v_pk_fma_f32 v[22:23], v[42:43], v[118:119], v[22:23] op_sel_hi:[1,0,1]
	v_pk_fma_f32 v[24:25], v[44:45], v[118:119], v[24:25] op_sel_hi:[1,0,1]
	v_add_f32_dpp v31, v32, v32 row_mirror row_mask:0xf bank_mask:0xf bound_ctrl:1
	v_add_f32_dpp v32, v30, v30 row_ror:8 row_mask:0xf bank_mask:0xf bound_ctrl:1
	v_mov_b32_e32 v30, v107
	v_mov_b32_e32 v108, v119
	s_waitcnt lgkmcnt(14)
	v_pk_mul_f32 v[118:119], v[106:107], v[122:123]
	v_pk_fma_f32 v[106:107], v[88:89], v[30:31], v[24:25] op_sel_hi:[1,0,1]
	v_pk_fma_f32 v[120:121], v[86:87], v[30:31], v[22:23] op_sel_hi:[1,0,1]
	v_add_f32_e32 v109, v118, v31
	v_pk_mul_f32 v[34:35], v[34:35], v[120:121]
	v_pk_mul_f32 v[36:37], v[36:37], v[106:107]
	v_sub_f32_e32 v118, v109, v119
	v_pk_mul_f32 v[16:17], v[16:17], v[106:107]
	v_pk_fma_f32 v[36:37], v[64:65], v[108:109], v[36:37] op_sel_hi:[1,0,1]
	v_pk_fma_f32 v[34:35], v[62:63], v[108:109], v[34:35] op_sel_hi:[1,0,1]
	v_pk_fma_f32 v[14:15], v[14:15], v[120:121], v[16:17]
	v_pk_fma_f32 v[16:17], v[102:103], v[118:119], v[34:35] op_sel_hi:[1,0,1]
	v_pk_fma_f32 v[34:35], v[104:105], v[118:119], v[36:37] op_sel_hi:[1,0,1]
	v_add_f32_e32 v36, v14, v15
	v_pk_mul_f32 v[14:15], v[20:21], v[34:35]
	s_waitcnt lgkmcnt(4)
	ds_write_b32 v6, v32 offset:896
	ds_read_b128 v[22:25], v8 offset:5120
	ds_read_b128 v[30:33], v8 offset:5376
	ds_read_b128 v[38:41], v8 offset:13312
	ds_read_b128 v[42:45], v8 offset:13568
	ds_read_b128 v[50:53], v8 offset:21504
	ds_read_b128 v[66:69], v8 offset:21760
	ds_read_b128 v[70:73], v8 offset:29696
	ds_read_b128 v[74:77], v8 offset:29952
	ds_read_b128 v[86:89], v8 offset:37888
	ds_read_b128 v[98:101], v8 offset:38144
	ds_read2_b32 v[122:123], v9 offset0:64 offset1:80
	v_pk_mul_f32 v[20:21], v[80:81], v[34:35]
	v_add_f32_dpp v62, v36, v36 quad_perm:[1,0,3,2] row_mask:0xf bank_mask:0xf bound_ctrl:1
	s_waitcnt lgkmcnt(15)
	v_pk_mul_f32 v[36:37], v[84:85], v[34:35]
	v_pk_fma_f32 v[14:15], v[18:19], v[16:17], v[14:15]
	v_pk_fma_f32 v[18:19], v[78:79], v[16:17], v[20:21]
	v_pk_mul_f32 v[26:27], v[26:27], v[16:17]
	v_pk_fma_f32 v[16:17], v[82:83], v[16:17], v[36:37]
	v_add_f32_e32 v14, v14, v15
	v_add_f32_e32 v15, v18, v19
	v_add_f32_e32 v16, v16, v17
	v_add_f32_dpp v14, v14, v14 quad_perm:[1,0,3,2] row_mask:0xf bank_mask:0xf bound_ctrl:1
	v_add_f32_dpp v15, v15, v15 quad_perm:[1,0,3,2] row_mask:0xf bank_mask:0xf bound_ctrl:1
	v_add_f32_dpp v16, v16, v16 quad_perm:[1,0,3,2] row_mask:0xf bank_mask:0xf bound_ctrl:1
	v_cndmask_b32_e32 v14, v14, v62, vcc
	v_add_f32_dpp v15, v15, v15 quad_perm:[2,3,0,1] row_mask:0xf bank_mask:0xf bound_ctrl:1
	v_add_f32_dpp v16, v16, v16 quad_perm:[2,3,0,1] row_mask:0xf bank_mask:0xf bound_ctrl:1
	v_add_f32_dpp v14, v14, v14 row_ror:2 row_mask:0xf bank_mask:0xf bound_ctrl:1
	v_add_f32_dpp v15, v15, v15 row_half_mirror row_mask:0xf bank_mask:0xf bound_ctrl:1
	v_pk_mul_f32 v[28:29], v[28:29], v[34:35]
	v_add_f32_dpp v16, v16, v16 row_half_mirror row_mask:0xf bank_mask:0xf bound_ctrl:1
	v_add_f32_dpp v14, v14, v14 row_ror:4 row_mask:0xf bank_mask:0xf bound_ctrl:1
	v_add_f32_dpp v111, v15, v15 row_mirror row_mask:0xf bank_mask:0xf bound_ctrl:1
	s_waitcnt lgkmcnt(12)
	v_mov_b32_e32 v110, v126
	v_pk_fma_f32 v[20:21], v[54:55], v[126:127], v[26:27] op_sel_hi:[1,0,1]
	v_pk_fma_f32 v[26:27], v[56:57], v[126:127], v[28:29] op_sel_hi:[1,0,1]
	v_add_f32_dpp v15, v16, v16 row_mirror row_mask:0xf bank_mask:0xf bound_ctrl:1
	v_add_f32_dpp v16, v14, v14 row_ror:8 row_mask:0xf bank_mask:0xf bound_ctrl:1
	v_mov_b32_e32 v14, v111
	v_pk_mul_f32 v[114:115], v[110:111], v[114:115]
	v_pk_fma_f32 v[110:111], v[92:93], v[14:15], v[26:27] op_sel_hi:[1,0,1]
	v_pk_fma_f32 v[118:119], v[90:91], v[14:15], v[20:21] op_sel_hi:[1,0,1]
	v_mov_b32_e32 v112, v127
	v_add_f32_e32 v107, v114, v15
	v_pk_mul_f32 v[46:47], v[46:47], v[118:119]
	v_pk_mul_f32 v[48:49], v[48:49], v[110:111]
	v_sub_f32_e32 v114, v107, v115
	v_pk_mul_f32 v[2:3], v[2:3], v[110:111]
	v_pk_fma_f32 v[48:49], v[60:61], v[112:113], v[48:49] op_sel_hi:[1,0,1]
	v_pk_fma_f32 v[46:47], v[58:59], v[112:113], v[46:47] op_sel_hi:[1,0,1]
	v_pk_fma_f32 v[0:1], v[0:1], v[118:119], v[2:3]
	v_pk_fma_f32 v[2:3], v[94:95], v[114:115], v[46:47] op_sel_hi:[1,0,1]
	v_pk_fma_f32 v[46:47], v[96:97], v[114:115], v[48:49] op_sel_hi:[1,0,1]
	v_add_f32_e32 v48, v0, v1
	v_pk_mul_f32 v[0:1], v[12:13], v[46:47]
	s_waitcnt lgkmcnt(4)
	ds_write_b32 v6, v16 offset:1024
	ds_read_b128 v[14:17], v8 offset:5632
	ds_read_b128 v[18:21], v8 offset:5888
	ds_read_b128 v[26:29], v8 offset:13824
	ds_read_b128 v[34:37], v8 offset:14080
	ds_read_b128 v[54:57], v8 offset:22016
	ds_read_b128 v[62:65], v8 offset:22272
	ds_read_b128 v[78:81], v8 offset:30208
	ds_read_b128 v[82:85], v8 offset:30464
	ds_read_b128 v[90:93], v8 offset:38400
	ds_read_b128 v[102:105], v8 offset:38656
	ds_read2_b32 v[120:121], v9 offset0:96 offset1:112
	ds_read_b64 v[124:125], v7 offset:43096
	v_pk_mul_f32 v[12:13], v[72:73], v[46:47]
	v_add_f32_dpp v58, v48, v48 quad_perm:[1,0,3,2] row_mask:0xf bank_mask:0xf bound_ctrl:1
	s_waitcnt lgkmcnt(15)
; template <int CTRL> __device__ __forceinline__ float dppf(float x) { return __builtin_bit_cast(float, __builtin_amdgcn_mov_dpp(__builtin_bit_cast(int, x), CTRL, 0xf, 0xf, true)); }
; __device__ __forceinline__ void scan_unit(const Params& p, int unit) {
;     ...
;             for (int pr = 0; pr < SC_TC / 2; ++pr) {
;                 const int sn = 2 * pr + 2;
;                 const f32x4 r1n = SC_LD(0, sn), w1n = SC_LD(1, sn), k1n = SC_LD(2, sn), q1n = SC_LD(3, sn), n1n = SC_LD(4, sn);
;                 const f32x4 r2n = SC_LD(0, sn + 1), w2n = SC_LD(1, sn + 1), k2n = SC_LD(2, sn + 1), g2n = SC_LD(3, sn + 1), n2n = SC_LD(4, sn + 1);
;                 const float v1n = buf[SC_VOFF + sn * 16 + rl], v2n = buf[SC_VOFF + (sn + 1) * 16 + rl];
;                 const f32x2 cfn = *(const f32x2*)(buf + SC_COFF + (pr + 1) * 2);
;                 __builtin_amdgcn_sched_barrier(0x7);
;                 float d1 = dot4(S, q1), e2 = dot4(S, g2);
;                 const f32x4 t1 = S * w1 + v1 * k1;
;                 reduce16x2(d1, e2);
;                 const float d2 = e2 + v1 * cf[0] - d1 * cf[1];
;                 const f32x4 S1 = t1 + d1 * n1;
;                 const f32x4 S2 = (S1 * w2 + v2 * k2) + d2 * n2;
;                 float y1 = dot4(S1, r1), y2 = dot4(S2, r2);
;                 y1 += dppf<0xB1>(y1); y2 += dppf<0xB1>(y2);
;                 float yz = odd_lane ? y2 : y1;
;                 yz += dppf<0x122>(yz); yz += dppf<0x124>(yz); yz += dppf<0x128>(yz);
;                 yb[(2 * pr) * 16 + yoff] = yz;
;                 S = S2;
;                 r1 = r1n; w1 = w1n; k1 = k1n; q1 = q1n; n1 = n1n; r2 = r2n; w2 = w2n; k2 = k2n; g2 = g2n; n2 = n2n; v1 = v1n; v2 = v2n; cf = cfn;
	v_pk_mul_f32 v[48:49], v[76:77], v[46:47]
	v_pk_fma_f32 v[0:1], v[10:11], v[2:3], v[0:1]
	v_pk_fma_f32 v[10:11], v[70:71], v[2:3], v[12:13]
	v_pk_mul_f32 v[38:39], v[38:39], v[2:3]
	v_pk_fma_f32 v[2:3], v[74:75], v[2:3], v[48:49]
	v_add_f32_e32 v0, v0, v1
	v_add_f32_e32 v1, v10, v11
	v_add_f32_e32 v2, v2, v3
	v_add_f32_dpp v0, v0, v0 quad_perm:[1,0,3,2] row_mask:0xf bank_mask:0xf bound_ctrl:1
	v_add_f32_dpp v1, v1, v1 quad_perm:[1,0,3,2] row_mask:0xf bank_mask:0xf bound_ctrl:1
	v_add_f32_dpp v2, v2, v2 quad_perm:[1,0,3,2] row_mask:0xf bank_mask:0xf bound_ctrl:1
	v_cndmask_b32_e32 v0, v0, v58, vcc
	v_add_f32_dpp v1, v1, v1 quad_perm:[2,3,0,1] row_mask:0xf bank_mask:0xf bound_ctrl:1
	v_add_f32_dpp v2, v2, v2 quad_perm:[2,3,0,1] row_mask:0xf bank_mask:0xf bound_ctrl:1
	v_add_f32_dpp v0, v0, v0 row_ror:2 row_mask:0xf bank_mask:0xf bound_ctrl:1
	v_add_f32_dpp v1, v1, v1 row_half_mirror row_mask:0xf bank_mask:0xf bound_ctrl:1
	v_pk_mul_f32 v[40:41], v[40:41], v[46:47]
	v_add_f32_dpp v2, v2, v2 row_half_mirror row_mask:0xf bank_mask:0xf bound_ctrl:1
	v_add_f32_dpp v0, v0, v0 row_ror:4 row_mask:0xf bank_mask:0xf bound_ctrl:1
	v_add_f32_dpp v107, v1, v1 row_mirror row_mask:0xf bank_mask:0xf bound_ctrl:1
	s_waitcnt lgkmcnt(13)
	v_mov_b32_e32 v106, v122
	v_pk_fma_f32 v[12:13], v[50:51], v[122:123], v[38:39] op_sel_hi:[1,0,1]
	v_pk_fma_f32 v[38:39], v[52:53], v[122:123], v[40:41] op_sel_hi:[1,0,1]
	v_add_f32_dpp v1, v2, v2 row_mirror row_mask:0xf bank_mask:0xf bound_ctrl:1
	v_add_f32_dpp v2, v0, v0 row_ror:8 row_mask:0xf bank_mask:0xf bound_ctrl:1
	v_mov_b32_e32 v0, v107
	v_pk_mul_f32 v[114:115], v[106:107], v[116:117]
	v_pk_fma_f32 v[106:107], v[88:89], v[0:1], v[38:39] op_sel_hi:[1,0,1]
	v_pk_fma_f32 v[116:117], v[86:87], v[0:1], v[12:13] op_sel_hi:[1,0,1]
	v_mov_b32_e32 v108, v123
	v_add_f32_e32 v109, v114, v1
	v_pk_mul_f32 v[42:43], v[42:43], v[116:117]
	v_pk_mul_f32 v[44:45], v[44:45], v[106:107]
	v_sub_f32_e32 v114, v109, v115
	v_pk_mul_f32 v[24:25], v[24:25], v[106:107]
	v_pk_fma_f32 v[44:45], v[68:69], v[108:109], v[44:45] op_sel_hi:[1,0,1]
	v_pk_fma_f32 v[42:43], v[66:67], v[108:109], v[42:43] op_sel_hi:[1,0,1]
	v_pk_fma_f32 v[22:23], v[22:23], v[116:117], v[24:25]
	v_pk_fma_f32 v[24:25], v[98:99], v[114:115], v[42:43] op_sel_hi:[1,0,1]
	v_pk_fma_f32 v[42:43], v[100:101], v[114:115], v[44:45] op_sel_hi:[1,0,1]
	v_add_f32_e32 v44, v22, v23
	v_pk_mul_f32 v[22:23], v[32:33], v[42:43]
	s_waitcnt lgkmcnt(5)
	ds_write_b32 v6, v2 offset:1152
	ds_read_b128 v[0:3], v8 offset:6144
	ds_read_b128 v[10:13], v8 offset:6400
	ds_read_b128 v[38:41], v8 offset:14336
	ds_read_b128 v[46:49], v8 offset:14592
	ds_read_b128 v[50:53], v8 offset:22528
	ds_read_b128 v[58:61], v8 offset:22784
	ds_read_b128 v[70:73], v8 offset:30720
	ds_read_b128 v[74:77], v8 offset:30976
	ds_read_b128 v[86:89], v8 offset:38912
	ds_read_b128 v[94:97], v8 offset:39168
	ds_read2_b32 v[118:119], v9 offset0:128 offset1:144
	ds_read_b64 v[122:123], v7 offset:43104
	v_pk_mul_f32 v[32:33], v[80:81], v[42:43]
	v_pk_fma_f32 v[22:23], v[30:31], v[24:25], v[22:23]
	v_pk_fma_f32 v[30:31], v[78:79], v[24:25], v[32:33]
	v_add_f32_dpp v66, v44, v44 quad_perm:[1,0,3,2] row_mask:0xf bank_mask:0xf bound_ctrl:1
	s_waitcnt lgkmcnt(15)
	v_pk_mul_f32 v[44:45], v[84:85], v[42:43]
	v_add_f32_e32 v22, v22, v23
	v_add_f32_e32 v23, v30, v31
	v_pk_mul_f32 v[26:27], v[26:27], v[24:25]
	v_pk_fma_f32 v[24:25], v[82:83], v[24:25], v[44:45]
	v_add_f32_dpp v22, v22, v22 quad_perm:[1,0,3,2] row_mask:0xf bank_mask:0xf bound_ctrl:1
	v_add_f32_dpp v23, v23, v23 quad_perm:[1,0,3,2] row_mask:0xf bank_mask:0xf bound_ctrl:1
	v_add_f32_e32 v24, v24, v25
	v_cndmask_b32_e32 v22, v22, v66, vcc
	v_add_f32_dpp v23, v23, v23 quad_perm:[2,3,0,1] row_mask:0xf bank_mask:0xf bound_ctrl:1
	v_add_f32_dpp v24, v24, v24 quad_perm:[1,0,3,2] row_mask:0xf bank_mask:0xf bound_ctrl:1
	v_add_f32_dpp v22, v22, v22 row_ror:2 row_mask:0xf bank_mask:0xf bound_ctrl:1
	v_add_f32_dpp v23, v23, v23 row_half_mirror row_mask:0xf bank_mask:0xf bound_ctrl:1
	v_pk_mul_f32 v[28:29], v[28:29], v[42:43]
	v_add_f32_dpp v24, v24, v24 quad_perm:[2,3,0,1] row_mask:0xf bank_mask:0xf bound_ctrl:1
	v_add_f32_dpp v22, v22, v22 row_ror:4 row_mask:0xf bank_mask:0xf bound_ctrl:1
	v_add_f32_dpp v111, v23, v23 row_mirror row_mask:0xf bank_mask:0xf bound_ctrl:1
	s_waitcnt lgkmcnt(14)
	v_mov_b32_e32 v110, v120
	v_pk_fma_f32 v[26:27], v[54:55], v[120:121], v[26:27] op_sel_hi:[1,0,1]
	v_pk_fma_f32 v[28:29], v[56:57], v[120:121], v[28:29] op_sel_hi:[1,0,1]
	v_add_f32_dpp v24, v24, v24 row_half_mirror row_mask:0xf bank_mask:0xf bound_ctrl:1
	v_add_f32_dpp v23, v22, v22 row_ror:8 row_mask:0xf bank_mask:0xf bound_ctrl:1
	v_mov_b32_e32 v22, v111
	v_mov_b32_e32 v112, v121
	v_add_f32_dpp v107, v24, v24 row_mirror row_mask:0xf bank_mask:0xf bound_ctrl:1
	s_waitcnt lgkmcnt(13)
	v_pk_mul_f32 v[110:111], v[110:111], v[124:125]
	v_pk_fma_f32 v[120:121], v[92:93], v[22:23], v[28:29] op_sel_hi:[1,0,1]
	v_pk_fma_f32 v[124:125], v[90:91], v[22:23], v[26:27] op_sel_hi:[1,0,1]
	v_add_f32_e32 v107, v110, v107
	v_pk_mul_f32 v[34:35], v[34:35], v[124:125]
	v_pk_mul_f32 v[36:37], v[36:37], v[120:121]
	v_pk_mul_f32 v[16:17], v[16:17], v[120:121]
	v_sub_f32_e32 v110, v107, v111
	v_pk_fma_f32 v[36:37], v[64:65], v[112:113], v[36:37] op_sel_hi:[1,0,1]
	v_pk_fma_f32 v[34:35], v[62:63], v[112:113], v[34:35] op_sel_hi:[1,0,1]
	v_pk_fma_f32 v[14:15], v[14:15], v[124:125], v[16:17]
	v_pk_fma_f32 v[16:17], v[102:103], v[110:111], v[34:35] op_sel_hi:[1,0,1]
	v_pk_fma_f32 v[34:35], v[104:105], v[110:111], v[36:37] op_sel_hi:[1,0,1]
	v_add_f32_e32 v36, v14, v15
	v_pk_mul_f32 v[14:15], v[20:21], v[34:35]
	s_waitcnt lgkmcnt(5)
; template <int CTRL> __device__ __forceinline__ float dppf(float x) { return __builtin_bit_cast(float, __builtin_amdgcn_mov_dpp(__builtin_bit_cast(int, x), CTRL, 0xf, 0xf, true)); }
; __device__ __forceinline__ void scan_unit(const Params& p, int unit) {
;     ...
;             for (int pr = 0; pr < SC_TC / 2; ++pr) {
;                 const int sn = 2 * pr + 2;
;                 const f32x4 r1n = SC_LD(0, sn), w1n = SC_LD(1, sn), k1n = SC_LD(2, sn), q1n = SC_LD(3, sn), n1n = SC_LD(4, sn);
;                 const f32x4 r2n = SC_LD(0, sn + 1), w2n = SC_LD(1, sn + 1), k2n = SC_LD(2, sn + 1), g2n = SC_LD(3, sn + 1), n2n = SC_LD(4, sn + 1);
;                 const float v1n = buf[SC_VOFF + sn * 16 + rl], v2n = buf[SC_VOFF + (sn + 1) * 16 + rl];
;                 const f32x2 cfn = *(const f32x2*)(buf + SC_COFF + (pr + 1) * 2);
;                 __builtin_amdgcn_sched_barrier(0x7);
;                 float d1 = dot4(S, q1), e2 = dot4(S, g2);
;                 const f32x4 t1 = S * w1 + v1 * k1;
;                 reduce16x2(d1, e2);
;                 const float d2 = e2 + v1 * cf[0] - d1 * cf[1];
;                 const f32x4 S1 = t1 + d1 * n1;
;                 const f32x4 S2 = (S1 * w2 + v2 * k2) + d2 * n2;
;                 float y1 = dot4(S1, r1), y2 = dot4(S2, r2);
;                 y1 += dppf<0xB1>(y1); y2 += dppf<0xB1>(y2);
;                 float yz = odd_lane ? y2 : y1;
;                 yz += dppf<0x122>(yz); yz += dppf<0x124>(yz); yz += dppf<0x128>(yz);
;                 yb[(2 * pr) * 16 + yoff] = yz;
;                 S = S2;
;                 r1 = r1n; w1 = w1n; k1 = k1n; q1 = q1n; n1 = n1n; r2 = r2n; w2 = w2n; k2 = k2n; g2 = g2n; n2 = n2n; v1 = v1n; v2 = v2n; cf = cfn;
	v_pk_mul_f32 v[20:21], v[72:73], v[34:35]
	v_add_f32_dpp v62, v36, v36 quad_perm:[1,0,3,2] row_mask:0xf bank_mask:0xf bound_ctrl:1
	s_waitcnt lgkmcnt(4)
	ds_write_b32 v6, v23 offset:1280
	ds_read_b64 v[114:115], v7 offset:43112
	ds_read_b64 v[116:117], v7 offset:43120
	ds_read_b128 v[22:25], v8 offset:6656
	ds_read_b128 v[26:29], v8 offset:6912
	ds_read_b128 v[30:33], v8 offset:14848
	ds_read_b128 v[42:45], v8 offset:15104
	ds_read_b128 v[54:57], v8 offset:23040
	ds_read_b128 v[66:69], v8 offset:23296
	ds_read_b128 v[78:81], v8 offset:31232
	ds_read_b128 v[82:85], v8 offset:31488
	ds_read_b128 v[90:93], v8 offset:39424
	ds_read_b128 v[98:101], v8 offset:39680
	ds_read2_b32 v[126:127], v9 offset0:160 offset1:176
	v_pk_mul_f32 v[36:37], v[76:77], v[34:35]
	v_pk_fma_f32 v[14:15], v[18:19], v[16:17], v[14:15]
	v_pk_fma_f32 v[18:19], v[70:71], v[16:17], v[20:21]
	v_pk_mul_f32 v[38:39], v[38:39], v[16:17]
	v_pk_fma_f32 v[16:17], v[74:75], v[16:17], v[36:37]
	v_add_f32_e32 v14, v14, v15
	v_add_f32_e32 v15, v18, v19
	v_add_f32_e32 v16, v16, v17
	v_add_f32_dpp v14, v14, v14 quad_perm:[1,0,3,2] row_mask:0xf bank_mask:0xf bound_ctrl:1
	v_add_f32_dpp v15, v15, v15 quad_perm:[1,0,3,2] row_mask:0xf bank_mask:0xf bound_ctrl:1
	v_add_f32_dpp v16, v16, v16 quad_perm:[1,0,3,2] row_mask:0xf bank_mask:0xf bound_ctrl:1
	v_cndmask_b32_e32 v14, v14, v62, vcc
	v_add_f32_dpp v15, v15, v15 quad_perm:[2,3,0,1] row_mask:0xf bank_mask:0xf bound_ctrl:1
	v_add_f32_dpp v16, v16, v16 quad_perm:[2,3,0,1] row_mask:0xf bank_mask:0xf bound_ctrl:1
	v_add_f32_dpp v14, v14, v14 row_ror:2 row_mask:0xf bank_mask:0xf bound_ctrl:1
	v_add_f32_dpp v15, v15, v15 row_half_mirror row_mask:0xf bank_mask:0xf bound_ctrl:1
	v_pk_mul_f32 v[34:35], v[40:41], v[34:35]
	v_add_f32_dpp v16, v16, v16 row_half_mirror row_mask:0xf bank_mask:0xf bound_ctrl:1
	v_add_f32_dpp v14, v14, v14 row_ror:4 row_mask:0xf bank_mask:0xf bound_ctrl:1
	v_add_f32_dpp v107, v15, v15 row_mirror row_mask:0xf bank_mask:0xf bound_ctrl:1
	s_waitcnt lgkmcnt(15)
	v_mov_b32_e32 v106, v118
	v_pk_fma_f32 v[20:21], v[50:51], v[118:119], v[38:39] op_sel_hi:[1,0,1]
	v_pk_fma_f32 v[34:35], v[52:53], v[118:119], v[34:35] op_sel_hi:[1,0,1]
	v_add_f32_dpp v15, v16, v16 row_mirror row_mask:0xf bank_mask:0xf bound_ctrl:1
	v_add_f32_dpp v16, v14, v14 row_ror:8 row_mask:0xf bank_mask:0xf bound_ctrl:1
	v_mov_b32_e32 v14, v107
	v_mov_b32_e32 v108, v119
	s_waitcnt lgkmcnt(14)
	v_pk_mul_f32 v[118:119], v[106:107], v[122:123]
	v_pk_fma_f32 v[106:107], v[88:89], v[14:15], v[34:35] op_sel_hi:[1,0,1]
	v_pk_fma_f32 v[120:121], v[86:87], v[14:15], v[20:21] op_sel_hi:[1,0,1]
	v_add_f32_e32 v109, v118, v15
	v_pk_mul_f32 v[46:47], v[46:47], v[120:121]
	v_pk_mul_f32 v[48:49], v[48:49], v[106:107]
	v_sub_f32_e32 v118, v109, v119
	v_pk_mul_f32 v[2:3], v[2:3], v[106:107]
	v_pk_fma_f32 v[48:49], v[60:61], v[108:109], v[48:49] op_sel_hi:[1,0,1]
	v_pk_fma_f32 v[46:47], v[58:59], v[108:109], v[46:47] op_sel_hi:[1,0,1]
	v_pk_fma_f32 v[0:1], v[0:1], v[120:121], v[2:3]
	v_pk_fma_f32 v[2:3], v[94:95], v[118:119], v[46:47] op_sel_hi:[1,0,1]
	v_pk_fma_f32 v[46:47], v[96:97], v[118:119], v[48:49] op_sel_hi:[1,0,1]
	v_add_f32_e32 v48, v0, v1
	v_pk_mul_f32 v[0:1], v[12:13], v[46:47]
	s_waitcnt lgkmcnt(4)
	ds_write_b32 v6, v16 offset:1408
	ds_read_b128 v[14:17], v8 offset:7168
	ds_read_b128 v[18:21], v8 offset:7424
	ds_read_b128 v[34:37], v8 offset:15360
	ds_read_b128 v[38:41], v8 offset:15616
	ds_read_b128 v[50:53], v8 offset:23552
	ds_read_b128 v[62:65], v8 offset:23808
	ds_read_b128 v[70:73], v8 offset:31744
	ds_read_b128 v[74:77], v8 offset:32000
	ds_read_b128 v[86:89], v8 offset:39936
	ds_read_b128 v[102:105], v8 offset:40192
	ds_read2_b32 v[122:123], v9 offset0:192 offset1:208
	v_pk_mul_f32 v[12:13], v[80:81], v[46:47]
	v_add_f32_dpp v58, v48, v48 quad_perm:[1,0,3,2] row_mask:0xf bank_mask:0xf bound_ctrl:1
	s_waitcnt lgkmcnt(15)
	v_pk_mul_f32 v[48:49], v[84:85], v[46:47]
	v_pk_fma_f32 v[0:1], v[10:11], v[2:3], v[0:1]
	v_pk_fma_f32 v[10:11], v[78:79], v[2:3], v[12:13]
	v_pk_mul_f32 v[30:31], v[30:31], v[2:3]
	v_pk_fma_f32 v[2:3], v[82:83], v[2:3], v[48:49]
	v_add_f32_e32 v0, v0, v1
	v_add_f32_e32 v1, v10, v11
	v_add_f32_e32 v2, v2, v3
	v_add_f32_dpp v0, v0, v0 quad_perm:[1,0,3,2] row_mask:0xf bank_mask:0xf bound_ctrl:1
	v_add_f32_dpp v1, v1, v1 quad_perm:[1,0,3,2] row_mask:0xf bank_mask:0xf bound_ctrl:1
	v_add_f32_dpp v2, v2, v2 quad_perm:[1,0,3,2] row_mask:0xf bank_mask:0xf bound_ctrl:1
	v_cndmask_b32_e32 v0, v0, v58, vcc
	v_add_f32_dpp v1, v1, v1 quad_perm:[2,3,0,1] row_mask:0xf bank_mask:0xf bound_ctrl:1
	v_add_f32_dpp v2, v2, v2 quad_perm:[2,3,0,1] row_mask:0xf bank_mask:0xf bound_ctrl:1
	v_add_f32_dpp v0, v0, v0 row_ror:2 row_mask:0xf bank_mask:0xf bound_ctrl:1
	v_add_f32_dpp v1, v1, v1 row_half_mirror row_mask:0xf bank_mask:0xf bound_ctrl:1
	v_pk_mul_f32 v[32:33], v[32:33], v[46:47]
	v_add_f32_dpp v2, v2, v2 row_half_mirror row_mask:0xf bank_mask:0xf bound_ctrl:1
	v_add_f32_dpp v0, v0, v0 row_ror:4 row_mask:0xf bank_mask:0xf bound_ctrl:1
	v_add_f32_dpp v111, v1, v1 row_mirror row_mask:0xf bank_mask:0xf bound_ctrl:1
	s_waitcnt lgkmcnt(12)
; template <int CTRL> __device__ __forceinline__ float dppf(float x) { return __builtin_bit_cast(float, __builtin_amdgcn_mov_dpp(__builtin_bit_cast(int, x), CTRL, 0xf, 0xf, true)); }
; __device__ __forceinline__ void scan_unit(const Params& p, int unit) {
;     ...
;             for (int pr = 0; pr < SC_TC / 2; ++pr) {
;                 const int sn = 2 * pr + 2;
;                 const f32x4 r1n = SC_LD(0, sn), w1n = SC_LD(1, sn), k1n = SC_LD(2, sn), q1n = SC_LD(3, sn), n1n = SC_LD(4, sn);
;                 const f32x4 r2n = SC_LD(0, sn + 1), w2n = SC_LD(1, sn + 1), k2n = SC_LD(2, sn + 1), g2n = SC_LD(3, sn + 1), n2n = SC_LD(4, sn + 1);
;                 const float v1n = buf[SC_VOFF + sn * 16 + rl], v2n = buf[SC_VOFF + (sn + 1) * 16 + rl];
;                 const f32x2 cfn = *(const f32x2*)(buf + SC_COFF + (pr + 1) * 2);
;                 __builtin_amdgcn_sched_barrier(0x7);
;                 float d1 = dot4(S, q1), e2 = dot4(S, g2);
;                 const f32x4 t1 = S * w1 + v1 * k1;
;                 reduce16x2(d1, e2);
;                 const float d2 = e2 + v1 * cf[0] - d1 * cf[1];
;                 const f32x4 S1 = t1 + d1 * n1;
;                 const f32x4 S2 = (S1 * w2 + v2 * k2) + d2 * n2;
;                 float y1 = dot4(S1, r1), y2 = dot4(S2, r2);
;                 y1 += dppf<0xB1>(y1); y2 += dppf<0xB1>(y2);
;                 float yz = odd_lane ? y2 : y1;
;                 yz += dppf<0x122>(yz); yz += dppf<0x124>(yz); yz += dppf<0x128>(yz);
;                 yb[(2 * pr) * 16 + yoff] = yz;
;                 S = S2;
;                 r1 = r1n; w1 = w1n; k1 = k1n; q1 = q1n; n1 = n1n; r2 = r2n; w2 = w2n; k2 = k2n; g2 = g2n; n2 = n2n; v1 = v1n; v2 = v2n; cf = cfn;
	v_mov_b32_e32 v110, v126
	v_pk_fma_f32 v[12:13], v[54:55], v[126:127], v[30:31] op_sel_hi:[1,0,1]
	v_pk_fma_f32 v[30:31], v[56:57], v[126:127], v[32:33] op_sel_hi:[1,0,1]
	v_add_f32_dpp v1, v2, v2 row_mirror row_mask:0xf bank_mask:0xf bound_ctrl:1
	v_add_f32_dpp v2, v0, v0 row_ror:8 row_mask:0xf bank_mask:0xf bound_ctrl:1
	v_mov_b32_e32 v0, v111
	v_pk_mul_f32 v[114:115], v[110:111], v[114:115]
	v_pk_fma_f32 v[110:111], v[92:93], v[0:1], v[30:31] op_sel_hi:[1,0,1]
	v_pk_fma_f32 v[118:119], v[90:91], v[0:1], v[12:13] op_sel_hi:[1,0,1]
	v_mov_b32_e32 v112, v127
	v_add_f32_e32 v107, v114, v1
	v_pk_mul_f32 v[42:43], v[42:43], v[118:119]
	v_pk_mul_f32 v[44:45], v[44:45], v[110:111]
	v_sub_f32_e32 v114, v107, v115
	v_pk_mul_f32 v[24:25], v[24:25], v[110:111]
	v_pk_fma_f32 v[44:45], v[68:69], v[112:113], v[44:45] op_sel_hi:[1,0,1]
	v_pk_fma_f32 v[42:43], v[66:67], v[112:113], v[42:43] op_sel_hi:[1,0,1]
	ds_write_b32 v6, v2 offset:1536
	v_pk_fma_f32 v[22:23], v[22:23], v[118:119], v[24:25]
	v_pk_fma_f32 v[24:25], v[98:99], v[114:115], v[42:43] op_sel_hi:[1,0,1]
	v_pk_fma_f32 v[42:43], v[100:101], v[114:115], v[44:45] op_sel_hi:[1,0,1]
	ds_read_b128 v[0:3], v8 offset:7680
	ds_read_b128 v[10:13], v8 offset:7936
	ds_read_b128 v[30:33], v8 offset:15872
	ds_read_b128 v[46:49], v8 offset:16128
	ds_read_b128 v[54:57], v8 offset:24064
	ds_read_b128 v[58:61], v8 offset:24320
	ds_read_b128 v[78:81], v8 offset:32256
	ds_read_b128 v[82:85], v8 offset:32512
	ds_read_b128 v[90:93], v8 offset:40448
	ds_read_b128 v[94:97], v8 offset:40704
	ds_read2_b32 v[8:9], v9 offset0:224 offset1:240
	ds_read_b64 v[120:121], v7 offset:43128
	v_add_f32_e32 v7, v22, v23
	v_pk_mul_f32 v[22:23], v[28:29], v[42:43]
	s_waitcnt lgkmcnt(14)
	v_pk_mul_f32 v[28:29], v[72:73], v[42:43]
	v_pk_mul_f32 v[44:45], v[76:77], v[42:43]
	v_pk_fma_f32 v[22:23], v[26:27], v[24:25], v[22:23]
	v_pk_fma_f32 v[26:27], v[70:71], v[24:25], v[28:29]
	v_pk_mul_f32 v[34:35], v[34:35], v[24:25]
	v_pk_fma_f32 v[24:25], v[74:75], v[24:25], v[44:45]
	v_add_f32_e32 v22, v22, v23
	v_add_f32_e32 v23, v26, v27
	v_add_f32_dpp v7, v7, v7 quad_perm:[1,0,3,2] row_mask:0xf bank_mask:0xf bound_ctrl:1
	v_add_f32_e32 v24, v24, v25
	v_add_f32_dpp v22, v22, v22 quad_perm:[1,0,3,2] row_mask:0xf bank_mask:0xf bound_ctrl:1
	v_add_f32_dpp v23, v23, v23 quad_perm:[1,0,3,2] row_mask:0xf bank_mask:0xf bound_ctrl:1
	v_add_f32_dpp v24, v24, v24 quad_perm:[1,0,3,2] row_mask:0xf bank_mask:0xf bound_ctrl:1
	v_cndmask_b32_e32 v7, v22, v7, vcc
	v_add_f32_dpp v22, v23, v23 quad_perm:[2,3,0,1] row_mask:0xf bank_mask:0xf bound_ctrl:1
	v_add_f32_dpp v23, v24, v24 quad_perm:[2,3,0,1] row_mask:0xf bank_mask:0xf bound_ctrl:1
	v_add_f32_dpp v7, v7, v7 row_ror:2 row_mask:0xf bank_mask:0xf bound_ctrl:1
	v_add_f32_dpp v22, v22, v22 row_half_mirror row_mask:0xf bank_mask:0xf bound_ctrl:1
	s_waitcnt lgkmcnt(13)
	v_mov_b32_e32 v106, v122
	v_pk_mul_f32 v[36:37], v[36:37], v[42:43]
	v_add_f32_dpp v23, v23, v23 row_half_mirror row_mask:0xf bank_mask:0xf bound_ctrl:1
	v_add_f32_dpp v7, v7, v7 row_ror:4 row_mask:0xf bank_mask:0xf bound_ctrl:1
	v_add_f32_dpp v107, v22, v22 row_mirror row_mask:0xf bank_mask:0xf bound_ctrl:1
	v_pk_fma_f32 v[28:29], v[50:51], v[122:123], v[34:35] op_sel_hi:[1,0,1]
	v_pk_fma_f32 v[34:35], v[52:53], v[122:123], v[36:37] op_sel_hi:[1,0,1]
	v_add_f32_dpp v25, v23, v23 row_mirror row_mask:0xf bank_mask:0xf bound_ctrl:1
	v_add_f32_dpp v7, v7, v7 row_ror:8 row_mask:0xf bank_mask:0xf bound_ctrl:1
	v_pk_mul_f32 v[22:23], v[106:107], v[116:117]
	v_mov_b32_e32 v24, v107
	ds_write_b32 v6, v7 offset:1664
	v_add_f32_e32 v7, v22, v25
	v_pk_fma_f32 v[26:27], v[88:89], v[24:25], v[34:35] op_sel_hi:[1,0,1]
	v_pk_fma_f32 v[24:25], v[86:87], v[24:25], v[28:29] op_sel_hi:[1,0,1]
	v_mov_b32_e32 v108, v123
	v_pk_mul_f32 v[28:29], v[38:39], v[24:25]
	v_pk_mul_f32 v[34:35], v[40:41], v[26:27]
	v_sub_f32_e32 v22, v7, v23
	v_pk_mul_f32 v[16:17], v[16:17], v[26:27]
	v_pk_fma_f32 v[26:27], v[64:65], v[108:109], v[34:35] op_sel_hi:[1,0,1]
	v_pk_fma_f32 v[28:29], v[62:63], v[108:109], v[28:29] op_sel_hi:[1,0,1]
	v_pk_fma_f32 v[14:15], v[14:15], v[24:25], v[16:17]
	v_pk_fma_f32 v[16:17], v[102:103], v[22:23], v[28:29] op_sel_hi:[1,0,1]
	v_pk_fma_f32 v[22:23], v[104:105], v[22:23], v[26:27] op_sel_hi:[1,0,1]
	v_add_f32_e32 v7, v14, v15
	v_pk_mul_f32 v[14:15], v[20:21], v[22:23]
	s_waitcnt lgkmcnt(6)
; template <int CTRL> __device__ __forceinline__ float dppf(float x) { return __builtin_bit_cast(float, __builtin_amdgcn_mov_dpp(__builtin_bit_cast(int, x), CTRL, 0xf, 0xf, true)); }
; __device__ __forceinline__ void scan_unit(const Params& p, int unit) {
;     ...
;             for (int pr = 0; pr < SC_TC / 2; ++pr) {
;                 const int sn = 2 * pr + 2;
;                 const f32x4 r1n = SC_LD(0, sn), w1n = SC_LD(1, sn), k1n = SC_LD(2, sn), q1n = SC_LD(3, sn), n1n = SC_LD(4, sn);
;                 const f32x4 r2n = SC_LD(0, sn + 1), w2n = SC_LD(1, sn + 1), k2n = SC_LD(2, sn + 1), g2n = SC_LD(3, sn + 1), n2n = SC_LD(4, sn + 1);
;                 const float v1n = buf[SC_VOFF + sn * 16 + rl], v2n = buf[SC_VOFF + (sn + 1) * 16 + rl];
;                 const f32x2 cfn = *(const f32x2*)(buf + SC_COFF + (pr + 1) * 2);
;                 __builtin_amdgcn_sched_barrier(0x7);
;                 float d1 = dot4(S, q1), e2 = dot4(S, g2);
;                 const f32x4 t1 = S * w1 + v1 * k1;
;                 reduce16x2(d1, e2);
;                 const float d2 = e2 + v1 * cf[0] - d1 * cf[1];
;                 const f32x4 S1 = t1 + d1 * n1;
;                 const f32x4 S2 = (S1 * w2 + v2 * k2) + d2 * n2;
;                 float y1 = dot4(S1, r1), y2 = dot4(S2, r2);
;                 y1 += dppf<0xB1>(y1); y2 += dppf<0xB1>(y2);
;                 float yz = odd_lane ? y2 : y1;
;                 yz += dppf<0x122>(yz); yz += dppf<0x124>(yz); yz += dppf<0x128>(yz);
;                 yb[(2 * pr) * 16 + yoff] = yz;
;                 S = S2;
;                 r1 = r1n; w1 = w1n; k1 = k1n; q1 = q1n; n1 = n1n; r2 = r2n; w2 = w2n; k2 = k2n; g2 = g2n; n2 = n2n; v1 = v1n; v2 = v2n; cf = cfn;
;             }
;     ...
;             __syncthreads();
;         }
	v_pk_mul_f32 v[20:21], v[80:81], v[22:23]
	s_waitcnt lgkmcnt(5)
	v_pk_mul_f32 v[24:25], v[84:85], v[22:23]
	v_pk_fma_f32 v[14:15], v[18:19], v[16:17], v[14:15]
	v_pk_fma_f32 v[18:19], v[78:79], v[16:17], v[20:21]
	v_pk_mul_f32 v[26:27], v[30:31], v[16:17]
	v_pk_fma_f32 v[16:17], v[82:83], v[16:17], v[24:25]
	v_add_f32_e32 v14, v14, v15
	v_add_f32_e32 v15, v18, v19
	v_add_f32_dpp v7, v7, v7 quad_perm:[1,0,3,2] row_mask:0xf bank_mask:0xf bound_ctrl:1
	v_add_f32_e32 v16, v16, v17
	v_add_f32_dpp v14, v14, v14 quad_perm:[1,0,3,2] row_mask:0xf bank_mask:0xf bound_ctrl:1
	v_add_f32_dpp v15, v15, v15 quad_perm:[1,0,3,2] row_mask:0xf bank_mask:0xf bound_ctrl:1
	v_add_f32_dpp v16, v16, v16 quad_perm:[1,0,3,2] row_mask:0xf bank_mask:0xf bound_ctrl:1
	v_cndmask_b32_e32 v7, v14, v7, vcc
	v_add_f32_dpp v14, v15, v15 quad_perm:[2,3,0,1] row_mask:0xf bank_mask:0xf bound_ctrl:1
	v_add_f32_dpp v15, v16, v16 quad_perm:[2,3,0,1] row_mask:0xf bank_mask:0xf bound_ctrl:1
	v_pk_mul_f32 v[22:23], v[32:33], v[22:23]
	v_add_f32_dpp v14, v14, v14 row_half_mirror row_mask:0xf bank_mask:0xf bound_ctrl:1
	v_add_f32_dpp v7, v7, v7 row_ror:2 row_mask:0xf bank_mask:0xf bound_ctrl:1
	v_add_f32_dpp v15, v15, v15 row_half_mirror row_mask:0xf bank_mask:0xf bound_ctrl:1
	v_add_f32_dpp v37, v14, v14 row_mirror row_mask:0xf bank_mask:0xf bound_ctrl:1
	s_waitcnt lgkmcnt(2)
	v_mov_b32_e32 v36, v8
	v_mov_b32_e32 v42, v9
	v_pk_fma_f32 v[20:21], v[54:55], v[8:9], v[26:27] op_sel_hi:[1,0,1]
	v_pk_fma_f32 v[8:9], v[56:57], v[8:9], v[22:23] op_sel_hi:[1,0,1]
	v_add_f32_dpp v7, v7, v7 row_ror:4 row_mask:0xf bank_mask:0xf bound_ctrl:1
	v_add_f32_dpp v17, v15, v15 row_mirror row_mask:0xf bank_mask:0xf bound_ctrl:1
	v_mov_b32_e32 v16, v37
	v_add_f32_dpp v7, v7, v7 row_ror:8 row_mask:0xf bank_mask:0xf bound_ctrl:1
	s_waitcnt lgkmcnt(1)
	v_pk_mul_f32 v[14:15], v[36:37], v[120:121]
	v_pk_fma_f32 v[8:9], v[92:93], v[16:17], v[8:9] op_sel_hi:[1,0,1]
	ds_write_b32 v6, v7 offset:1792
	v_add_f32_e32 v7, v14, v17
	v_pk_fma_f32 v[16:17], v[90:91], v[16:17], v[20:21] op_sel_hi:[1,0,1]
	v_pk_mul_f32 v[20:21], v[48:49], v[8:9]
	v_sub_f32_e32 v14, v7, v15
	v_pk_mul_f32 v[18:19], v[46:47], v[16:17]
	v_pk_mul_f32 v[2:3], v[2:3], v[8:9]
	v_pk_fma_f32 v[8:9], v[60:61], v[42:43], v[20:21] op_sel_hi:[1,0,1]
	v_pk_fma_f32 v[18:19], v[58:59], v[42:43], v[18:19] op_sel_hi:[1,0,1]
	v_pk_fma_f32 v[16:17], v[0:1], v[16:17], v[2:3]
	v_pk_fma_f32 v[2:3], v[96:97], v[14:15], v[8:9] op_sel_hi:[1,0,1]
	v_pk_fma_f32 v[0:1], v[94:95], v[14:15], v[18:19] op_sel_hi:[1,0,1]
	v_pk_mul_f32 v[8:9], v[12:13], v[2:3]
	v_add_f32_e32 v7, v16, v17
	v_pk_fma_f32 v[8:9], v[10:11], v[0:1], v[8:9]
	s_add_i32 s4, s4, 1
	v_add_f32_e32 v8, v8, v9
	v_add_f32_dpp v7, v7, v7 quad_perm:[1,0,3,2] row_mask:0xf bank_mask:0xf bound_ctrl:1
	s_cmpk_eq_i32 s4, 0x101
	v_add_f32_dpp v8, v8, v8 quad_perm:[1,0,3,2] row_mask:0xf bank_mask:0xf bound_ctrl:1
	v_cndmask_b32_e32 v7, v8, v7, vcc
	s_nop 1
	v_add_f32_dpp v7, v7, v7 row_ror:2 row_mask:0xf bank_mask:0xf bound_ctrl:1
	s_nop 1
	v_add_f32_dpp v7, v7, v7 row_ror:4 row_mask:0xf bank_mask:0xf bound_ctrl:1
	s_nop 1
	v_add_f32_dpp v7, v7, v7 row_ror:8 row_mask:0xf bank_mask:0xf bound_ctrl:1
	ds_write_b32 v6, v7 offset:1920
	s_waitcnt lgkmcnt(0)
	s_barrier
	s_cbranch_scc0 .LBB0_786
	s_setprio 0

; __device__ __forceinline__ void attn_unit(const Params& p, int unit) {
;     ...
;         const int kb = kt - 1 + half;
;         const bool done = __all(Arow > zb) || kb < 0;
;         if (lane == 0) flags[wave] = done ? 1 : 0;
;         __syncthreads();
;         int alld = 1;
; #pragma unroll
;         for (int w = 0; w < 8; ++w) alld &= flags[w];
;         if (alld) break;
;         if (kt >= 1) {
.LBB0_824:
	v_add3_u32 v32, v65, v55, -1
	s_mov_b64 s[8:9], exec
	v_cmp_gt_f32_e64 s[0:1], v88, v57
	v_cmp_gt_i32_e64 s[6:7], 0, v32
	v_cmp_lt_i32_e64 s[4:5], -1, v32
	s_and_saveexec_b64 s[10:11], s[40:41]
	s_cbranch_execz .LBB0_826
	s_cmp_eq_u64 s[0:1], s[8:9]
	s_cselect_b64 s[0:1], -1, 0
	s_or_b64 s[0:1], s[0:1], s[6:7]
	v_cndmask_b32_e64 v33, 0, 1, s[0:1]
	ds_write_b32 v50, v33
.LBB0_826:
	s_or_b64 exec, exec, s[10:11]
	s_cmp_lg_u32 s75, -1
	s_cselect_b32 s0, s75, 0
	s_cselect_b32 s1, s55, 0
	s_cmp_lg_u32 s76, -1
	v_mov_b32_e32 v34, s0
	v_mov_b32_e32 v35, s1
	s_cselect_b32 s0, s76, 0
	s_cselect_b32 s1, s55, 0
	s_cmp_lg_u32 s77, -1
	s_waitcnt lgkmcnt(0)
	s_barrier
	v_mov_b32_e32 v35, s75
	ds_read_b32 v33, v35
	ds_read_b32 v36, v35 offset:4
	ds_read_b32 v37, v35 offset:8
	ds_read_b32 v38, v35 offset:12
	ds_read_b32 v39, v35 offset:16
	ds_read_b32 v40, v35 offset:20
	ds_read_b32 v41, v35 offset:24
	ds_read_b32 v34, v35 offset:28
	s_waitcnt vmcnt(0)
	v_add_u32_e32 v89, -1, v55
	v_mov_b32_e32 v97, 11
	s_waitcnt lgkmcnt(0)
	v_bitop3_b32 v33, v33, v37, v36 bitop3:0x80
	v_bitop3_b32 v33, v33, v39, v38 bitop3:0x80
	v_bitop3_b32 v33, v33, v41, v40 bitop3:0x80
	v_bitop3_b32 v33, v33, 1, v34 bitop3:0x80
	v_cmp_eq_u32_e64 s[0:1], 0, v33
	s_and_saveexec_b64 s[68:69], s[0:1]
	s_cbranch_execz .LBB0_890
	v_cmp_ne_u32_e64 s[0:1], 0, v55
	s_and_saveexec_b64 s[6:7], s[0:1]
	s_cbranch_execz .LBB0_831
	v_and_b32_e32 v33, 1, v89
	v_cmp_eq_u32_e64 s[0:1], 1, v33
	v_lshlrev_b32_e32 v34, 1, v66
	s_nop 0
	v_cndmask_b32_e64 v33, 0, v79, s[0:1]
	v_add_u32_e32 v33, 0, v33
	v_add3_u32 v34, v33, v34, v48
	v_lshl_add_u32 v33, v68, 1, v33
	v_cmp_lt_i32_e64 s[0:1], 1, v55
	ds_write_b128 v34, v[28:31]
	ds_write_b16 v33, v24 offset:9216
	ds_write_b16_d16_hi v33, v24 offset:9360
	ds_write_b16 v33, v25 offset:9504
	ds_write_b16_d16_hi v33, v25 offset:9648
	ds_write_b16 v33, v26 offset:9792
	ds_write_b16_d16_hi v33, v26 offset:9936
	ds_write_b16 v33, v27 offset:10080
	ds_write_b16_d16_hi v33, v27 offset:10224
	s_and_saveexec_b64 s[8:9], s[0:1]
	s_cbranch_execz .LBB0_830
	v_add_u32_e32 v24, s48, v85
	v_ashrrev_i32_e32 v25, 31, v24
	v_lshlrev_b64 v[24:25], 7, v[24:25]
	v_lshl_add_u64 v[26:27], v[60:61], 0, v[24:25]
	v_lshl_add_u64 v[24:25], v[62:63], 0, v[24:25]
	global_load_dwordx4 v[28:31], v[26:27], off
	s_nop 0
	global_load_dwordx4 v[24:27], v[24:25], off
